# GEMM tiles: second-stage LDS-DMA issued in the tile prologue right behind the first stage (vmcnt(8) wait), redundant prologue vmcnt(0) dropped
# speedup vs baseline: 1.0022x; 1.0013x over previous
; DI void vm_wait0() { asm volatile("s_waitcnt vmcnt(0)" ::: "memory"); }
;   DI unsigned rowoff(int m) const { int combo = m >> 9, n = m & 511, b = combo >> 1, g = combo & 1; return (unsigned)((b * SEQ + 16 * n) * EIN + col0 + g * 64); }
;   DI unsigned koff(int k) const { return (unsigned)((k >> 6) * EIN + (k & 63)); }
; DI void dma16(const void* g, unsigned char* l) { __builtin_amdgcn_global_load_lds((const unsigned*)g, (lds_u32_t*)(unsigned)(size_t)l, 16, 0, 0); }
; template <class AF, class EF>
; DI void gemm_run(unsigned char* lds, int wv, const AF& af, const bf16_t* __restrict__ Bt, int ldb, int M, int N, int K, const EF& ef, int blk_off) {
;     ...
;   for (int tile_ = first; tile_ < ntl_eff; tile_ += tstep) {
;     int nt, mt;
;     if (xmap) { nt = tile_ % ntiles; mt = (tile_ / ntiles) * 8 + ((int)blockIdx.x & 7); }
;     else { nt = tile_ % ntiles; mt = tile_ / ntiles; }
;     const int m0 = mt << 8, n0 = nt << 8;
;     f32x4 acc[4][8];
; #pragma unroll
;     for (int i = 0; i < 4; ++i)
; #pragma unroll
;       for (int j = 0; j < 8; ++j) acc[i][j] = (f32x4){0.f, 0.f, 0.f, 0.f};
;     unsigned aoff[4], boff[4];
;     const bf16_t* Ab = af.base();
; #pragma unroll
;     for (int i = 0; i < 4; ++i) {
;       int row = crow + 64 * i;
;       aoff[i] = af.rowoff(m0 + row);
;       int n = n0 + row; n = n < N ? n : N - 1;
;       boff[i] = (unsigned)(n * ldb + cch);
;     }
;     __syncthreads();
; #pragma unroll
;     for (int i = 0; i < 4; ++i) {
;       dma16(Ab + aoff[i] + af.koff(cch), sBase + 32768 + (i * 512 + tid) * 16);
;       dma16(Bt + boff[i], sBase + (i * 512 + tid) * 16);
;     }
;     vm_wait0();
.LBB0_119:
	s_mul_hi_i32 s4, s2, 0x2aaaaaab
	s_lshr_b32 s5, s4, 31
	s_ashr_i32 s4, s4, 1
	s_add_i32 s7, s4, s5
	s_lshl_b32 s4, s7, 3
	s_or_b32 s6, s4, s78
	v_readlane_b32 s4, v254, 34
	v_readlane_b32 s5, v254, 35
	s_and_b64 s[4:5], s[4:5], exec
	s_cselect_b32 s4, s6, s7
	s_mul_i32 s7, s7, 12
	s_lshl_b32 s6, s4, 8
	s_sub_i32 s4, s2, s7
	s_lshl_b32 s7, s4, 8
	v_add_u32_e32 v3, s7, v164
	v_min_i32_e32 v3, 0xbff, v3
	v_lshl_or_b32 v6, v3, 10, v141
	v_add_u32_e32 v3, s7, v165
	v_min_i32_e32 v3, 0xbff, v3
	v_add_u32_e32 v2, s7, v139
	v_lshl_or_b32 v10, v3, 10, v141
	v_add_u32_e32 v3, s7, v166
	v_add_lshl_u32 v0, s6, v139, 10
	v_min_i32_e32 v2, 0xbff, v2
	v_min_i32_e32 v3, 0xbff, v3
	v_lshl_or_b32 v2, v2, 10, v141
	v_lshl_or_b32 v14, v3, 10, v141
	v_lshlrev_b64 v[16:17], 1, v[0:1]
	v_readfirstlane_b32 s4, v167
	v_mov_b32_e32 v3, v1
	v_add_lshl_u32 v4, s6, v164, 10
	v_lshl_add_u64 v[18:19], v[134:135], 0, v[16:17]
	s_mov_b32 m0, s4
	v_lshlrev_b64 v[2:3], 1, v[2:3]
	v_readfirstlane_b32 s4, v168
	v_mov_b32_e32 v5, v1
	s_waitcnt lgkmcnt(0)
	s_barrier
	global_load_lds_dwordx4 v[18:19], off
	v_lshl_add_u64 v[18:19], s[8:9], 0, v[2:3]
	s_mov_b32 m0, s4
	v_lshlrev_b64 v[4:5], 1, v[4:5]
	v_readfirstlane_b32 s4, v169
	v_mov_b32_e32 v7, v1
	v_add_lshl_u32 v8, s6, v165, 10
	global_load_lds_dwordx4 v[18:19], off
	v_lshl_add_u64 v[18:19], v[134:135], 0, v[4:5]
	s_mov_b32 m0, s4
	v_lshlrev_b64 v[6:7], 1, v[6:7]
	v_readfirstlane_b32 s4, v170
	v_mov_b32_e32 v9, v1
	global_load_lds_dwordx4 v[18:19], off
	v_lshl_add_u64 v[18:19], s[8:9], 0, v[6:7]
	s_mov_b32 m0, s4
	v_lshlrev_b64 v[8:9], 1, v[8:9]
	v_readfirstlane_b32 s4, v171
	v_mov_b32_e32 v11, v1
	v_add_lshl_u32 v12, s6, v166, 10
	global_load_lds_dwordx4 v[18:19], off
	v_lshl_add_u64 v[18:19], v[134:135], 0, v[8:9]
	s_mov_b32 m0, s4
	v_lshlrev_b64 v[10:11], 1, v[10:11]
	v_readfirstlane_b32 s4, v172
	v_mov_b32_e32 v13, v1
	global_load_lds_dwordx4 v[18:19], off
	v_lshl_add_u64 v[18:19], s[8:9], 0, v[10:11]
	s_mov_b32 m0, s4
	v_lshlrev_b64 v[12:13], 1, v[12:13]
	v_readfirstlane_b32 s4, v173
	v_mov_b32_e32 v15, v1
	global_load_lds_dwordx4 v[18:19], off
	v_lshl_add_u64 v[18:19], v[134:135], 0, v[12:13]
	s_mov_b32 m0, s4
	v_lshlrev_b64 v[14:15], 1, v[14:15]
	v_readfirstlane_b32 s4, v174
	global_load_lds_dwordx4 v[18:19], off
	v_lshl_add_u64 v[18:19], s[8:9], 0, v[14:15]
	s_mov_b32 m0, s4
	v_lshl_add_u64 v[152:153], s[12:13], 0, v[2:3]
	global_load_lds_dwordx4 v[18:19], off
	v_mov_b32_e32 v2, 0
	v_lshl_add_u64 v[146:147], s[12:13], 0, v[14:15]
	v_lshl_add_u64 v[148:149], s[12:13], 0, v[10:11]
	v_lshl_add_u64 v[150:151], s[12:13], 0, v[6:7]
	v_lshl_add_u64 v[154:155], v[144:145], 0, v[12:13]
	v_lshl_add_u64 v[156:157], v[144:145], 0, v[8:9]
	v_lshl_add_u64 v[158:159], v[144:145], 0, v[4:5]
	v_lshl_add_u64 v[160:161], v[144:145], 0, v[16:17]
	s_mov_b64 s[4:5], 0
	s_mov_b32 s14, 0x10000
	v_mov_b32_e32 v3, v2
	v_mov_b32_e32 v4, v2
	v_mov_b32_e32 v5, v2
	v_mov_b32_e32 v6, v2
	v_mov_b32_e32 v7, v2
	v_mov_b32_e32 v8, v2
	v_mov_b32_e32 v9, v2
	v_mov_b32_e32 v18, v2
	v_mov_b32_e32 v19, v2
	v_mov_b32_e32 v20, v2
	v_mov_b32_e32 v21, v2
	v_mov_b32_e32 v26, v2
	v_mov_b32_e32 v27, v2
	v_mov_b32_e32 v28, v2
	v_mov_b32_e32 v29, v2
	v_mov_b32_e32 v34, v2
	v_mov_b32_e32 v35, v2
	v_mov_b32_e32 v36, v2
	v_mov_b32_e32 v37, v2
	v_mov_b32_e32 v42, v2
	v_mov_b32_e32 v43, v2
	v_mov_b32_e32 v44, v2
	v_mov_b32_e32 v45, v2
	v_mov_b32_e32 v50, v2
	v_mov_b32_e32 v51, v2
	v_mov_b32_e32 v52, v2
	v_mov_b32_e32 v53, v2
	v_mov_b32_e32 v58, v2
	v_mov_b32_e32 v59, v2
	v_mov_b32_e32 v60, v2
	v_mov_b32_e32 v61, v2
	v_mov_b32_e32 v66, v2
	v_mov_b32_e32 v67, v2
	v_mov_b32_e32 v68, v2
	v_mov_b32_e32 v69, v2
	v_mov_b32_e32 v74, v2
	v_mov_b32_e32 v75, v2
	v_mov_b32_e32 v76, v2
	v_mov_b32_e32 v77, v2
	v_mov_b32_e32 v82, v2
	v_mov_b32_e32 v83, v2
	v_mov_b32_e32 v84, v2
	v_mov_b32_e32 v85, v2
	v_mov_b32_e32 v90, v2
	v_mov_b32_e32 v91, v2
	v_mov_b32_e32 v92, v2
	v_mov_b32_e32 v93, v2
	v_mov_b32_e32 v98, v2
	v_mov_b32_e32 v99, v2
	v_mov_b32_e32 v100, v2
	v_mov_b32_e32 v101, v2
	v_mov_b32_e32 v106, v2
	v_mov_b32_e32 v107, v2
	v_mov_b32_e32 v108, v2
	v_mov_b32_e32 v109, v2
	v_mov_b32_e32 v114, v2
	v_mov_b32_e32 v115, v2
	v_mov_b32_e32 v116, v2
	v_mov_b32_e32 v117, v2
	v_mov_b32_e32 v122, v2
	v_mov_b32_e32 v123, v2
	v_mov_b32_e32 v124, v2
	v_mov_b32_e32 v125, v2
	v_mov_b32_e32 v70, v2
	v_mov_b32_e32 v71, v2
	v_mov_b32_e32 v72, v2
	v_mov_b32_e32 v73, v2
	v_mov_b32_e32 v78, v2
	v_mov_b32_e32 v79, v2
	v_mov_b32_e32 v80, v2
	v_mov_b32_e32 v81, v2
	v_mov_b32_e32 v86, v2
	v_mov_b32_e32 v87, v2
	v_mov_b32_e32 v88, v2
	v_mov_b32_e32 v89, v2
	v_mov_b32_e32 v94, v2
	v_mov_b32_e32 v95, v2
	v_mov_b32_e32 v96, v2
	v_mov_b32_e32 v97, v2
	v_mov_b32_e32 v102, v2
	v_mov_b32_e32 v103, v2
	v_mov_b32_e32 v104, v2
	v_mov_b32_e32 v105, v2
	v_mov_b32_e32 v110, v2
	v_mov_b32_e32 v111, v2
	v_mov_b32_e32 v112, v2
	v_mov_b32_e32 v113, v2
	v_mov_b32_e32 v118, v2
	v_mov_b32_e32 v119, v2
	v_mov_b32_e32 v120, v2
	v_mov_b32_e32 v121, v2
	v_mov_b32_e32 v126, v2
	v_mov_b32_e32 v127, v2
	v_mov_b32_e32 v128, v2
	v_mov_b32_e32 v129, v2
	v_mov_b32_e32 v62, v2
	v_mov_b32_e32 v63, v2
	v_mov_b32_e32 v64, v2
	v_mov_b32_e32 v65, v2
	v_mov_b32_e32 v54, v2
	v_mov_b32_e32 v55, v2
	v_mov_b32_e32 v56, v2
	v_mov_b32_e32 v57, v2
	v_mov_b32_e32 v46, v2
	v_mov_b32_e32 v47, v2
	v_mov_b32_e32 v48, v2
	v_mov_b32_e32 v49, v2
	v_mov_b32_e32 v38, v2
	v_mov_b32_e32 v39, v2
	v_mov_b32_e32 v40, v2
	v_mov_b32_e32 v41, v2
	v_mov_b32_e32 v30, v2
	v_mov_b32_e32 v31, v2
	v_mov_b32_e32 v32, v2
	v_mov_b32_e32 v33, v2
	v_mov_b32_e32 v22, v2
	v_mov_b32_e32 v23, v2
	v_mov_b32_e32 v24, v2
	v_mov_b32_e32 v25, v2
	v_mov_b32_e32 v14, v2
; DI void vm_wait0() { asm volatile("s_waitcnt vmcnt(0)" ::: "memory"); }
;   DI unsigned koff(int k) const { return (unsigned)((k >> 6) * EIN + (k & 63)); }
; DI void dma16(const void* g, unsigned char* l) { __builtin_amdgcn_global_load_lds((const unsigned*)g, (lds_u32_t*)(unsigned)(size_t)l, 16, 0, 0); }
; template <class AF, class EF>
; DI void gemm_run(unsigned char* lds, int wv, const AF& af, const bf16_t* __restrict__ Bt, int ldb, int M, int N, int K, const EF& ef, int blk_off) {
;     ...
;     __syncthreads();
; #pragma unroll
;     for (int i = 0; i < 4; ++i) {
;       dma16(Ab + aoff[i] + af.koff(cch), sBase + 32768 + (i * 512 + tid) * 16);
;       dma16(Bt + boff[i], sBase + (i * 512 + tid) * 16);
;     }
;     vm_wait0();
;     __syncthreads();
; #pragma unroll 1
;     for (int kt = 0; kt < nk; ++kt) {
;       unsigned char* cur = sBase + (kt & 1) * GST;
;       if (kt + 1 < nk) {
;         unsigned char* nxt = sBase + ((kt + 1) & 1) * GST;
;         const int k0 = (kt + 1) << 6;
; #pragma unroll
;         for (int i = 0; i < 4; ++i) {
;           dma16(Ab + aoff[i] + af.koff(k0 + cch), nxt + 32768 + (i * 512 + tid) * 16);
;           dma16(Bt + boff[i] + (unsigned)k0, nxt + (i * 512 + tid) * 16);
;         }
;       }
; #pragma unroll
;       for (int ks = 0; ks < 2; ++ks) {
;         bf16x8 wf[4], xf[8];
; #pragma unroll
;         for (int i = 0; i < 4; ++i) wf[i] = *(const bf16x8*)(cur + (wn * 64 + i * 16 + l15) * 128 + (((ks * 4 + q4) ^ swz) * 16));
; #pragma unroll
;         for (int j = 0; j < 8; ++j) xf[j] = *(const bf16x8*)(cur + 32768 + (wm * 128 + j * 16 + l15) * 128 + (((ks * 4 + q4) ^ swz) * 16));
	v_mov_b32_e32 v15, v2
	v_mov_b32_e32 v16, v2
	v_mov_b32_e32 v17, v2
	v_mov_b32_e32 v10, v2
	v_mov_b32_e32 v11, v2
	v_mov_b32_e32 v12, v2
	v_mov_b32_e32 v13, v2
	s_and_b32 s15, s14, 0x10000
	s_add_i32 s15, s15, 0
	s_add_i32 s16, s15, 0x2000
	s_add_i32 s15, s15, 0xa000
	v_add_u32_e32 v224, s15, v136
	v_lshl_add_u64 v[222:223], v[160:161], 0, s[4:5]
	v_readfirstlane_b32 s17, v224
	v_add_u32_e32 v224, s16, v136
	s_mov_b32 m0, s17
	v_readfirstlane_b32 s17, v224
	v_add_u32_e32 v224, s15, v138
	global_load_lds_dwordx4 v[222:223], off
	v_lshl_add_u64 v[222:223], v[152:153], 0, s[4:5]
	s_mov_b32 m0, s17
	v_readfirstlane_b32 s17, v224
	v_add_u32_e32 v224, s16, v138
	global_load_lds_dwordx4 v[222:223], off
	v_lshl_add_u64 v[222:223], v[158:159], 0, s[4:5]
	s_mov_b32 m0, s17
	v_readfirstlane_b32 s17, v224
	v_add_u32_e32 v224, s15, v140
	global_load_lds_dwordx4 v[222:223], off
	v_lshl_add_u64 v[222:223], v[150:151], 0, s[4:5]
	s_mov_b32 m0, s17
	v_readfirstlane_b32 s17, v224
	v_add_u32_e32 v224, s16, v140
	global_load_lds_dwordx4 v[222:223], off
	v_lshl_add_u64 v[222:223], v[156:157], 0, s[4:5]
	s_mov_b32 m0, s17
	v_readfirstlane_b32 s17, v224
	v_add_u32_e32 v224, s15, v142
	global_load_lds_dwordx4 v[222:223], off
	v_lshl_add_u64 v[222:223], v[148:149], 0, s[4:5]
	s_mov_b32 m0, s17
	v_readfirstlane_b32 s15, v224
	v_add_u32_e32 v224, s16, v142
	global_load_lds_dwordx4 v[222:223], off
	v_lshl_add_u64 v[222:223], v[154:155], 0, s[4:5]
	s_mov_b32 m0, s15
	v_readfirstlane_b32 s15, v224
	global_load_lds_dwordx4 v[222:223], off
	v_lshl_add_u64 v[222:223], v[146:147], 0, s[4:5]
	s_mov_b32 m0, s15
	s_nop 0
	global_load_lds_dwordx4 v[222:223], off
	s_waitcnt vmcnt(8) lgkmcnt(0)
	s_barrier
	s_branch .LBB0_121
.LBB0_121:
	s_add_i32 s100, s14, 0xffff0000
	s_and_b32 s100, s100, 0x10000
	v_add_u32_e32 v0, s100, v175
	v_add3_u32 v212, v0, v176, v177
	v_add3_u32 v0, v0, v178, v177
	ds_read_b128 v[130:133], v212 offset:8192
	ds_read_b128 v[180:183], v0 offset:40960
	ds_read_b128 v[184:187], v0 offset:43008
	ds_read_b128 v[188:191], v0 offset:45056
	ds_read_b128 v[192:195], v0 offset:47104
	ds_read_b128 v[196:199], v0 offset:49152
	ds_read_b128 v[200:203], v0 offset:51200
	ds_read_b128 v[204:207], v0 offset:53248
	ds_read_b128 v[208:211], v0 offset:55296
; #define MFMA16(a, b, c) __builtin_amdgcn_mfma_f32_16x16x32_bf16((a), (b), (c), 0, 0, 0)
; DI void vm_wait0() { asm volatile("s_waitcnt vmcnt(0)" ::: "memory"); }
;   DI unsigned koff(int k) const { return (unsigned)((k >> 6) * EIN + (k & 63)); }
; DI void dma16(const void* g, unsigned char* l) { __builtin_amdgcn_global_load_lds((const unsigned*)g, (lds_u32_t*)(unsigned)(size_t)l, 16, 0, 0); }
; template <class AF, class EF>
; DI void gemm_run(unsigned char* lds, int wv, const AF& af, const bf16_t* __restrict__ Bt, int ldb, int M, int N, int K, const EF& ef, int blk_off) {
;     ...
;     for (int kt = 0; kt < nk; ++kt) {
;       unsigned char* cur = sBase + (kt & 1) * GST;
;       if (kt + 1 < nk) {
;         unsigned char* nxt = sBase + ((kt + 1) & 1) * GST;
;         const int k0 = (kt + 1) << 6;
; #pragma unroll
;         for (int i = 0; i < 4; ++i) {
;           dma16(Ab + aoff[i] + af.koff(k0 + cch), nxt + 32768 + (i * 512 + tid) * 16);
;           dma16(Bt + boff[i] + (unsigned)k0, nxt + (i * 512 + tid) * 16);
;         }
;       }
; #pragma unroll
;       for (int ks = 0; ks < 2; ++ks) {
;         bf16x8 wf[4], xf[8];
; #pragma unroll
;         for (int i = 0; i < 4; ++i) wf[i] = *(const bf16x8*)(cur + (wn * 64 + i * 16 + l15) * 128 + (((ks * 4 + q4) ^ swz) * 16));
; #pragma unroll
;         for (int j = 0; j < 8; ++j) xf[j] = *(const bf16x8*)(cur + 32768 + (wm * 128 + j * 16 + l15) * 128 + (((ks * 4 + q4) ^ swz) * 16));
; #pragma unroll
;         for (int i = 0; i < 4; ++i)
; #pragma unroll
;           for (int j = 0; j < 8; ++j) acc[i][j] = MFMA16(wf[i], xf[j], acc[i][j]);
;       }
;       vm_wait0();
;       __syncthreads();
;     }
.Lmyg120_loop:
	s_waitcnt lgkmcnt(7)
	v_mfma_f32_16x16x32_bf16 v[126:129], v[130:133], v[180:183], v[126:129]
	ds_read_b128 v[226:229], v212 offset:10240
	s_waitcnt lgkmcnt(7)
	v_mfma_f32_16x16x32_bf16 v[118:121], v[130:133], v[184:187], v[118:121]
	s_waitcnt lgkmcnt(6)
	v_mfma_f32_16x16x32_bf16 v[110:113], v[130:133], v[188:191], v[110:113]
	s_waitcnt lgkmcnt(5)
	v_mfma_f32_16x16x32_bf16 v[102:105], v[130:133], v[192:195], v[102:105]
	s_waitcnt lgkmcnt(4)
	v_mfma_f32_16x16x32_bf16 v[94:97], v[130:133], v[196:199], v[94:97]
	s_waitcnt lgkmcnt(3)
	v_mfma_f32_16x16x32_bf16 v[86:89], v[130:133], v[200:203], v[86:89]
	s_waitcnt lgkmcnt(2)
	v_mfma_f32_16x16x32_bf16 v[78:81], v[130:133], v[204:207], v[78:81]
	s_waitcnt lgkmcnt(1)
	v_mfma_f32_16x16x32_bf16 v[70:73], v[130:133], v[208:211], v[70:73]
	s_waitcnt lgkmcnt(0)
	v_mfma_f32_16x16x32_bf16 v[122:125], v[226:229], v[180:183], v[122:125]
	ds_read_b128 v[130:133], v212 offset:12288
	v_mfma_f32_16x16x32_bf16 v[114:117], v[226:229], v[184:187], v[114:117]
	v_mfma_f32_16x16x32_bf16 v[106:109], v[226:229], v[188:191], v[106:109]
	v_mfma_f32_16x16x32_bf16 v[98:101], v[226:229], v[192:195], v[98:101]
	v_mfma_f32_16x16x32_bf16 v[90:93], v[226:229], v[196:199], v[90:93]
	v_mfma_f32_16x16x32_bf16 v[82:85], v[226:229], v[200:203], v[82:85]
	v_mfma_f32_16x16x32_bf16 v[74:77], v[226:229], v[204:207], v[74:77]
	v_mfma_f32_16x16x32_bf16 v[66:69], v[226:229], v[208:211], v[66:69]
	s_waitcnt lgkmcnt(0)
	v_mfma_f32_16x16x32_bf16 v[58:61], v[130:133], v[180:183], v[58:61]
	ds_read_b128 v[226:229], v212 offset:14336
	v_mfma_f32_16x16x32_bf16 v[50:53], v[130:133], v[184:187], v[50:53]
	v_add_u32_e32 v0, s100, v179
	v_mfma_f32_16x16x32_bf16 v[42:45], v[130:133], v[188:191], v[42:45]
	v_add3_u32 v212, v0, v176, v177
	v_mfma_f32_16x16x32_bf16 v[34:37], v[130:133], v[192:195], v[34:37]
	v_add3_u32 v0, v0, v178, v177
	v_mfma_f32_16x16x32_bf16 v[26:29], v[130:133], v[196:199], v[26:29]
	v_mfma_f32_16x16x32_bf16 v[18:21], v[130:133], v[200:203], v[18:21]
	v_mfma_f32_16x16x32_bf16 v[6:9], v[130:133], v[204:207], v[6:9]
	v_mfma_f32_16x16x32_bf16 v[2:5], v[130:133], v[208:211], v[2:5]
	s_waitcnt lgkmcnt(0)
	v_mfma_f32_16x16x32_bf16 v[62:65], v[226:229], v[180:183], v[62:65]
	ds_read_b128 v[130:133], v212 offset:8192
	ds_read_b128 v[180:183], v0 offset:40960
	v_mfma_f32_16x16x32_bf16 v[54:57], v[226:229], v[184:187], v[54:57]
	ds_read_b128 v[184:187], v0 offset:43008
	v_mfma_f32_16x16x32_bf16 v[46:49], v[226:229], v[188:191], v[46:49]
	ds_read_b128 v[188:191], v0 offset:45056
	v_mfma_f32_16x16x32_bf16 v[38:41], v[226:229], v[192:195], v[38:41]
	ds_read_b128 v[192:195], v0 offset:47104
	v_mfma_f32_16x16x32_bf16 v[30:33], v[226:229], v[196:199], v[30:33]
	ds_read_b128 v[196:199], v0 offset:49152
	v_mfma_f32_16x16x32_bf16 v[22:25], v[226:229], v[200:203], v[22:25]
	ds_read_b128 v[200:203], v0 offset:51200
	v_mfma_f32_16x16x32_bf16 v[14:17], v[226:229], v[204:207], v[14:17]
	ds_read_b128 v[204:207], v0 offset:53248
	v_mfma_f32_16x16x32_bf16 v[10:13], v[226:229], v[208:211], v[10:13]
	ds_read_b128 v[208:211], v0 offset:55296
	s_waitcnt lgkmcnt(7)
	v_mfma_f32_16x16x32_bf16 v[126:129], v[130:133], v[180:183], v[126:129]
	ds_read_b128 v[226:229], v212 offset:10240
	s_waitcnt lgkmcnt(7)
	v_mfma_f32_16x16x32_bf16 v[118:121], v[130:133], v[184:187], v[118:121]
	s_waitcnt lgkmcnt(6)
	v_mfma_f32_16x16x32_bf16 v[110:113], v[130:133], v[188:191], v[110:113]
	s_waitcnt lgkmcnt(5)
	v_mfma_f32_16x16x32_bf16 v[102:105], v[130:133], v[192:195], v[102:105]
	s_waitcnt lgkmcnt(4)
	v_mfma_f32_16x16x32_bf16 v[94:97], v[130:133], v[196:199], v[94:97]
	s_waitcnt lgkmcnt(3)
	v_mfma_f32_16x16x32_bf16 v[86:89], v[130:133], v[200:203], v[86:89]
	s_waitcnt lgkmcnt(2)
	v_mfma_f32_16x16x32_bf16 v[78:81], v[130:133], v[204:207], v[78:81]
	s_waitcnt lgkmcnt(1)
	v_mfma_f32_16x16x32_bf16 v[70:73], v[130:133], v[208:211], v[70:73]
	s_waitcnt lgkmcnt(0)
	v_mfma_f32_16x16x32_bf16 v[122:125], v[226:229], v[180:183], v[122:125]
	ds_read_b128 v[130:133], v212 offset:12288
	v_mfma_f32_16x16x32_bf16 v[114:117], v[226:229], v[184:187], v[114:117]
	v_mfma_f32_16x16x32_bf16 v[106:109], v[226:229], v[188:191], v[106:109]
	v_mfma_f32_16x16x32_bf16 v[98:101], v[226:229], v[192:195], v[98:101]
	v_mfma_f32_16x16x32_bf16 v[90:93], v[226:229], v[196:199], v[90:93]
	v_mfma_f32_16x16x32_bf16 v[82:85], v[226:229], v[200:203], v[82:85]
	v_mfma_f32_16x16x32_bf16 v[74:77], v[226:229], v[204:207], v[74:77]
	v_mfma_f32_16x16x32_bf16 v[66:69], v[226:229], v[208:211], v[66:69]
	s_waitcnt lgkmcnt(0)
	v_mfma_f32_16x16x32_bf16 v[58:61], v[130:133], v[180:183], v[58:61]
	ds_read_b128 v[226:229], v212 offset:14336
	v_mfma_f32_16x16x32_bf16 v[50:53], v[130:133], v[184:187], v[50:53]
	v_mfma_f32_16x16x32_bf16 v[42:45], v[130:133], v[188:191], v[42:45]
	v_mfma_f32_16x16x32_bf16 v[34:37], v[130:133], v[192:195], v[34:37]
	v_mfma_f32_16x16x32_bf16 v[26:29], v[130:133], v[196:199], v[26:29]
	v_mfma_f32_16x16x32_bf16 v[18:21], v[130:133], v[200:203], v[18:21]
	v_mfma_f32_16x16x32_bf16 v[6:9], v[130:133], v[204:207], v[6:9]
	v_mfma_f32_16x16x32_bf16 v[2:5], v[130:133], v[208:211], v[2:5]
	s_waitcnt vmcnt(0) lgkmcnt(0)
	s_barrier
	s_add_u32 s4, s4, 0x80
	s_addc_u32 s5, s5, 0
	s_add_i32 s14, s14, 0x10000
	s_cmpk_eq_i32 s4, 0x800
	s_cbranch_scc1 .Lmyg120_tail
	s_add_i32 s100, s14, 0xffff0000
	s_and_b32 s100, s100, 0x10000
	v_add_u32_e32 v0, s100, v175
	v_add3_u32 v212, v0, v176, v177
	v_add3_u32 v0, v0, v178, v177
	s_cmpk_eq_i32 s4, 0x780
	s_cbranch_scc1 .Lmyg120_nodma
	s_setprio 3
	s_and_b32 s15, s14, 0x10000
	s_add_i32 s15, s15, 0
	s_add_i32 s16, s15, 0x2000
	s_add_i32 s15, s15, 0xa000
	v_add_u32_e32 v224, s15, v136
	v_lshl_add_u64 v[222:223], v[160:161], 0, s[4:5]
	v_readfirstlane_b32 s17, v224
	v_add_u32_e32 v224, s16, v136
	s_mov_b32 m0, s17
	v_readfirstlane_b32 s17, v224
	v_add_u32_e32 v224, s15, v138
	global_load_lds_dwordx4 v[222:223], off
	v_lshl_add_u64 v[222:223], v[152:153], 0, s[4:5]
	s_mov_b32 m0, s17
	v_readfirstlane_b32 s17, v224
	v_add_u32_e32 v224, s16, v138
	global_load_lds_dwordx4 v[222:223], off
	v_lshl_add_u64 v[222:223], v[158:159], 0, s[4:5]
	s_mov_b32 m0, s17
	v_readfirstlane_b32 s17, v224
	v_add_u32_e32 v224, s15, v140
	global_load_lds_dwordx4 v[222:223], off
	v_lshl_add_u64 v[222:223], v[150:151], 0, s[4:5]
	s_mov_b32 m0, s17
	v_readfirstlane_b32 s17, v224
	v_add_u32_e32 v224, s16, v140
	global_load_lds_dwordx4 v[222:223], off
	v_lshl_add_u64 v[222:223], v[156:157], 0, s[4:5]
	s_mov_b32 m0, s17
	v_readfirstlane_b32 s17, v224
	v_add_u32_e32 v224, s15, v142
	global_load_lds_dwordx4 v[222:223], off
	v_lshl_add_u64 v[222:223], v[148:149], 0, s[4:5]
	s_mov_b32 m0, s17
	v_readfirstlane_b32 s15, v224
	v_add_u32_e32 v224, s16, v142
	global_load_lds_dwordx4 v[222:223], off
	v_lshl_add_u64 v[222:223], v[154:155], 0, s[4:5]
	s_mov_b32 m0, s15
	v_readfirstlane_b32 s15, v224
	global_load_lds_dwordx4 v[222:223], off
	v_lshl_add_u64 v[222:223], v[146:147], 0, s[4:5]
	s_mov_b32 m0, s15
	s_nop 0
	global_load_lds_dwordx4 v[222:223], off
	s_setprio 0

; DI void vm_wait0() { asm volatile("s_waitcnt vmcnt(0)" ::: "memory"); }
;   DI unsigned rowoff(int m) const { int combo = m >> 9, n = m & 511, b = combo >> 1, g = combo & 1; return (unsigned)((b * SEQ + 16 * n) * EIN + col0 + g * 64); }
;   DI unsigned koff(int k) const { return (unsigned)((k >> 6) * EIN + (k & 63)); }
; DI void dma16(const void* g, unsigned char* l) { __builtin_amdgcn_global_load_lds((const unsigned*)g, (lds_u32_t*)(unsigned)(size_t)l, 16, 0, 0); }
; template <class AF, class EF>
; DI void gemm_run(unsigned char* lds, int wv, const AF& af, const bf16_t* __restrict__ Bt, int ldb, int M, int N, int K, const EF& ef, int blk_off) {
;     ...
;   for (int tile_ = first; tile_ < ntl_eff; tile_ += tstep) {
;     int nt, mt;
;     if (xmap) { nt = tile_ % ntiles; mt = (tile_ / ntiles) * 8 + ((int)blockIdx.x & 7); }
;     else { nt = tile_ % ntiles; mt = tile_ / ntiles; }
;     const int m0 = mt << 8, n0 = nt << 8;
;     f32x4 acc[4][8];
; #pragma unroll
;     for (int i = 0; i < 4; ++i)
; #pragma unroll
;       for (int j = 0; j < 8; ++j) acc[i][j] = (f32x4){0.f, 0.f, 0.f, 0.f};
;     unsigned aoff[4], boff[4];
;     const bf16_t* Ab = af.base();
; #pragma unroll
;     for (int i = 0; i < 4; ++i) {
;       int row = crow + 64 * i;
;       aoff[i] = af.rowoff(m0 + row);
;       int n = n0 + row; n = n < N ? n : N - 1;
;       boff[i] = (unsigned)(n * ldb + cch);
;     }
;     __syncthreads();
; #pragma unroll
;     for (int i = 0; i < 4; ++i) {
;       dma16(Ab + aoff[i] + af.koff(cch), sBase + 32768 + (i * 512 + tid) * 16);
;       dma16(Bt + boff[i], sBase + (i * 512 + tid) * 16);
;     }
;     vm_wait0();
.LBB0_260:
	s_mul_hi_i32 s4, s2, 0x66666667
	s_lshr_b32 s5, s4, 31
	s_ashr_i32 s4, s4, 2
	s_add_i32 s6, s4, s5
	s_lshl_b32 s4, s6, 3
	s_or_b32 s7, s4, s78
	v_readlane_b32 s4, v254, 34
	v_readlane_b32 s5, v254, 35
	s_and_b64 s[4:5], s[4:5], exec
	s_cselect_b32 s4, s7, s6
	s_mul_i32 s6, s6, 10
	s_lshl_b32 s7, s4, 8
	s_sub_i32 s4, s2, s6
	s_lshl_b32 s6, s4, 8
	v_add_u32_e32 v3, s6, v164
	v_min_i32_e32 v3, 0x9df, v3
	v_lshl_or_b32 v6, v3, 10, v141
	v_add_u32_e32 v3, s6, v165
	v_min_i32_e32 v3, 0x9df, v3
	v_add_u32_e32 v2, s6, v139
	v_lshl_or_b32 v10, v3, 10, v141
	v_add_u32_e32 v3, s6, v166
	v_add_lshl_u32 v0, s7, v139, 10
	v_min_i32_e32 v2, 0x9df, v2
	v_min_i32_e32 v3, 0x9df, v3
	v_lshl_or_b32 v2, v2, 10, v141
	v_lshl_or_b32 v14, v3, 10, v141
	v_lshlrev_b64 v[16:17], 1, v[0:1]
	v_readfirstlane_b32 s4, v167
	v_mov_b32_e32 v3, v1
	v_add_lshl_u32 v4, s7, v164, 10
	v_lshl_add_u64 v[18:19], v[134:135], 0, v[16:17]
	s_mov_b32 m0, s4
	v_lshlrev_b64 v[2:3], 1, v[2:3]
	v_readfirstlane_b32 s4, v168
	v_mov_b32_e32 v5, v1
	s_waitcnt lgkmcnt(0)
	s_barrier
	global_load_lds_dwordx4 v[18:19], off
	v_lshl_add_u64 v[18:19], s[8:9], 0, v[2:3]
	s_mov_b32 m0, s4
	v_lshlrev_b64 v[4:5], 1, v[4:5]
	v_readfirstlane_b32 s4, v169
	v_mov_b32_e32 v7, v1
	v_add_lshl_u32 v8, s7, v165, 10
	global_load_lds_dwordx4 v[18:19], off
	v_lshl_add_u64 v[18:19], v[134:135], 0, v[4:5]
	s_mov_b32 m0, s4
	v_lshlrev_b64 v[6:7], 1, v[6:7]
	v_readfirstlane_b32 s4, v170
	v_mov_b32_e32 v9, v1
	global_load_lds_dwordx4 v[18:19], off
	v_lshl_add_u64 v[18:19], s[8:9], 0, v[6:7]
	s_mov_b32 m0, s4
	v_lshlrev_b64 v[8:9], 1, v[8:9]
	v_readfirstlane_b32 s4, v171
	v_mov_b32_e32 v11, v1
	v_add_lshl_u32 v12, s7, v166, 10
	global_load_lds_dwordx4 v[18:19], off
	v_lshl_add_u64 v[18:19], v[134:135], 0, v[8:9]
	s_mov_b32 m0, s4
	v_lshlrev_b64 v[10:11], 1, v[10:11]
	v_readfirstlane_b32 s4, v172
	v_mov_b32_e32 v13, v1
	global_load_lds_dwordx4 v[18:19], off
	v_lshl_add_u64 v[18:19], s[8:9], 0, v[10:11]
	s_mov_b32 m0, s4
	v_lshlrev_b64 v[12:13], 1, v[12:13]
	v_readfirstlane_b32 s4, v173
	v_mov_b32_e32 v15, v1
	global_load_lds_dwordx4 v[18:19], off
	v_lshl_add_u64 v[18:19], v[134:135], 0, v[12:13]
	s_mov_b32 m0, s4
	v_lshlrev_b64 v[14:15], 1, v[14:15]
	v_readfirstlane_b32 s4, v174
	global_load_lds_dwordx4 v[18:19], off
	v_lshl_add_u64 v[18:19], s[8:9], 0, v[14:15]
	s_mov_b32 m0, s4
	v_lshl_add_u64 v[152:153], s[14:15], 0, v[2:3]
	global_load_lds_dwordx4 v[18:19], off
	v_mov_b32_e32 v2, 0
	v_lshl_add_u64 v[146:147], s[14:15], 0, v[14:15]
	v_lshl_add_u64 v[148:149], s[14:15], 0, v[10:11]
	v_lshl_add_u64 v[150:151], s[14:15], 0, v[6:7]
	v_lshl_add_u64 v[154:155], v[144:145], 0, v[12:13]
	v_lshl_add_u64 v[156:157], v[144:145], 0, v[8:9]
	v_lshl_add_u64 v[158:159], v[144:145], 0, v[4:5]
	v_lshl_add_u64 v[160:161], v[144:145], 0, v[16:17]
	s_mov_b64 s[4:5], 0
	s_mov_b32 s16, 0x10000
	v_mov_b32_e32 v3, v2
	v_mov_b32_e32 v4, v2
	v_mov_b32_e32 v5, v2
	v_mov_b32_e32 v14, v2
	v_mov_b32_e32 v15, v2
	v_mov_b32_e32 v16, v2
	v_mov_b32_e32 v17, v2
	v_mov_b32_e32 v22, v2
	v_mov_b32_e32 v23, v2
	v_mov_b32_e32 v24, v2
	v_mov_b32_e32 v25, v2
	v_mov_b32_e32 v30, v2
	v_mov_b32_e32 v31, v2
	v_mov_b32_e32 v32, v2
	v_mov_b32_e32 v33, v2
	v_mov_b32_e32 v38, v2
	v_mov_b32_e32 v39, v2
	v_mov_b32_e32 v40, v2
	v_mov_b32_e32 v41, v2
	v_mov_b32_e32 v46, v2
	v_mov_b32_e32 v47, v2
	v_mov_b32_e32 v48, v2
	v_mov_b32_e32 v49, v2
	v_mov_b32_e32 v54, v2
	v_mov_b32_e32 v55, v2
	v_mov_b32_e32 v56, v2
	v_mov_b32_e32 v57, v2
	v_mov_b32_e32 v62, v2
	v_mov_b32_e32 v63, v2
	v_mov_b32_e32 v64, v2
	v_mov_b32_e32 v65, v2
	v_mov_b32_e32 v66, v2
	v_mov_b32_e32 v67, v2
	v_mov_b32_e32 v68, v2
	v_mov_b32_e32 v69, v2
	v_mov_b32_e32 v74, v2
	v_mov_b32_e32 v75, v2
	v_mov_b32_e32 v76, v2
	v_mov_b32_e32 v77, v2
	v_mov_b32_e32 v82, v2
	v_mov_b32_e32 v83, v2
	v_mov_b32_e32 v84, v2
	v_mov_b32_e32 v85, v2
	v_mov_b32_e32 v90, v2
	v_mov_b32_e32 v91, v2
	v_mov_b32_e32 v92, v2
	v_mov_b32_e32 v93, v2
	v_mov_b32_e32 v98, v2
	v_mov_b32_e32 v99, v2
	v_mov_b32_e32 v100, v2
	v_mov_b32_e32 v101, v2
	v_mov_b32_e32 v106, v2
	v_mov_b32_e32 v107, v2
	v_mov_b32_e32 v108, v2
	v_mov_b32_e32 v109, v2
	v_mov_b32_e32 v114, v2
	v_mov_b32_e32 v115, v2
	v_mov_b32_e32 v116, v2
	v_mov_b32_e32 v117, v2
	v_mov_b32_e32 v122, v2
	v_mov_b32_e32 v123, v2
	v_mov_b32_e32 v124, v2
	v_mov_b32_e32 v125, v2
	v_mov_b32_e32 v70, v2
	v_mov_b32_e32 v71, v2
	v_mov_b32_e32 v72, v2
	v_mov_b32_e32 v73, v2
	v_mov_b32_e32 v78, v2
	v_mov_b32_e32 v79, v2
	v_mov_b32_e32 v80, v2
	v_mov_b32_e32 v81, v2
	v_mov_b32_e32 v86, v2
	v_mov_b32_e32 v87, v2
	v_mov_b32_e32 v88, v2
	v_mov_b32_e32 v89, v2
	v_mov_b32_e32 v94, v2
	v_mov_b32_e32 v95, v2
	v_mov_b32_e32 v96, v2
	v_mov_b32_e32 v97, v2
	v_mov_b32_e32 v102, v2
	v_mov_b32_e32 v103, v2
	v_mov_b32_e32 v104, v2
	v_mov_b32_e32 v105, v2
	v_mov_b32_e32 v110, v2
	v_mov_b32_e32 v111, v2
	v_mov_b32_e32 v112, v2
	v_mov_b32_e32 v113, v2
	v_mov_b32_e32 v118, v2
	v_mov_b32_e32 v119, v2
	v_mov_b32_e32 v120, v2
	v_mov_b32_e32 v121, v2
	v_mov_b32_e32 v126, v2
	v_mov_b32_e32 v127, v2
	v_mov_b32_e32 v128, v2
	v_mov_b32_e32 v129, v2
	v_mov_b32_e32 v58, v2
	v_mov_b32_e32 v59, v2
	v_mov_b32_e32 v60, v2
	v_mov_b32_e32 v61, v2
	v_mov_b32_e32 v50, v2
	v_mov_b32_e32 v51, v2
	v_mov_b32_e32 v52, v2
	v_mov_b32_e32 v53, v2
	v_mov_b32_e32 v42, v2
	v_mov_b32_e32 v43, v2
	v_mov_b32_e32 v44, v2
	v_mov_b32_e32 v45, v2
	v_mov_b32_e32 v34, v2
	v_mov_b32_e32 v35, v2
	v_mov_b32_e32 v36, v2
	v_mov_b32_e32 v37, v2
	v_mov_b32_e32 v26, v2
	v_mov_b32_e32 v27, v2
	v_mov_b32_e32 v28, v2
	v_mov_b32_e32 v29, v2
	v_mov_b32_e32 v18, v2
	v_mov_b32_e32 v19, v2
	v_mov_b32_e32 v20, v2
	v_mov_b32_e32 v21, v2
	v_mov_b32_e32 v10, v2
; DI void vm_wait0() { asm volatile("s_waitcnt vmcnt(0)" ::: "memory"); }
;   DI unsigned koff(int k) const { return (unsigned)((k >> 6) * EIN + (k & 63)); }
; DI void dma16(const void* g, unsigned char* l) { __builtin_amdgcn_global_load_lds((const unsigned*)g, (lds_u32_t*)(unsigned)(size_t)l, 16, 0, 0); }
; template <class AF, class EF>
; DI void gemm_run(unsigned char* lds, int wv, const AF& af, const bf16_t* __restrict__ Bt, int ldb, int M, int N, int K, const EF& ef, int blk_off) {
;     ...
;     __syncthreads();
; #pragma unroll
;     for (int i = 0; i < 4; ++i) {
;       dma16(Ab + aoff[i] + af.koff(cch), sBase + 32768 + (i * 512 + tid) * 16);
;       dma16(Bt + boff[i], sBase + (i * 512 + tid) * 16);
;     }
;     vm_wait0();
;     __syncthreads();
; #pragma unroll 1
;     for (int kt = 0; kt < nk; ++kt) {
;       unsigned char* cur = sBase + (kt & 1) * GST;
;       if (kt + 1 < nk) {
;         unsigned char* nxt = sBase + ((kt + 1) & 1) * GST;
;         const int k0 = (kt + 1) << 6;
; #pragma unroll
;         for (int i = 0; i < 4; ++i) {
;           dma16(Ab + aoff[i] + af.koff(k0 + cch), nxt + 32768 + (i * 512 + tid) * 16);
;           dma16(Bt + boff[i] + (unsigned)k0, nxt + (i * 512 + tid) * 16);
;         }
;       }
; #pragma unroll
;       for (int ks = 0; ks < 2; ++ks) {
;         bf16x8 wf[4], xf[8];
; #pragma unroll
;         for (int i = 0; i < 4; ++i) wf[i] = *(const bf16x8*)(cur + (wn * 64 + i * 16 + l15) * 128 + (((ks * 4 + q4) ^ swz) * 16));
; #pragma unroll
;         for (int j = 0; j < 8; ++j) xf[j] = *(const bf16x8*)(cur + 32768 + (wm * 128 + j * 16 + l15) * 128 + (((ks * 4 + q4) ^ swz) * 16));
	v_mov_b32_e32 v11, v2
	v_mov_b32_e32 v12, v2
	v_mov_b32_e32 v13, v2
	v_mov_b32_e32 v6, v2
	v_mov_b32_e32 v7, v2
	v_mov_b32_e32 v8, v2
	v_mov_b32_e32 v9, v2
	s_and_b32 s17, s16, 0x10000
	s_add_i32 s17, s17, 0
	s_add_i32 s18, s17, 0x2000
	s_add_i32 s17, s17, 0xa000
	v_add_u32_e32 v224, s17, v136
	v_lshl_add_u64 v[222:223], v[160:161], 0, s[4:5]
	v_readfirstlane_b32 s19, v224
	v_add_u32_e32 v224, s18, v136
	s_mov_b32 m0, s19
	v_readfirstlane_b32 s19, v224
	v_add_u32_e32 v224, s17, v138
	global_load_lds_dwordx4 v[222:223], off
	v_lshl_add_u64 v[222:223], v[152:153], 0, s[4:5]
	s_mov_b32 m0, s19
	v_readfirstlane_b32 s19, v224
	v_add_u32_e32 v224, s18, v138
	global_load_lds_dwordx4 v[222:223], off
	v_lshl_add_u64 v[222:223], v[158:159], 0, s[4:5]
	s_mov_b32 m0, s19
	v_readfirstlane_b32 s19, v224
	v_add_u32_e32 v224, s17, v140
	global_load_lds_dwordx4 v[222:223], off
	v_lshl_add_u64 v[222:223], v[150:151], 0, s[4:5]
	s_mov_b32 m0, s19
	v_readfirstlane_b32 s19, v224
	v_add_u32_e32 v224, s18, v140
	global_load_lds_dwordx4 v[222:223], off
	v_lshl_add_u64 v[222:223], v[156:157], 0, s[4:5]
	s_mov_b32 m0, s19
	v_readfirstlane_b32 s19, v224
	v_add_u32_e32 v224, s17, v142
	global_load_lds_dwordx4 v[222:223], off
	v_lshl_add_u64 v[222:223], v[148:149], 0, s[4:5]
	s_mov_b32 m0, s19
	v_readfirstlane_b32 s17, v224
	v_add_u32_e32 v224, s18, v142
	global_load_lds_dwordx4 v[222:223], off
	v_lshl_add_u64 v[222:223], v[154:155], 0, s[4:5]
	s_mov_b32 m0, s17
	v_readfirstlane_b32 s17, v224
	global_load_lds_dwordx4 v[222:223], off
	v_lshl_add_u64 v[222:223], v[146:147], 0, s[4:5]
	s_mov_b32 m0, s17
	s_nop 0
	global_load_lds_dwordx4 v[222:223], off
	s_waitcnt vmcnt(8) lgkmcnt(0)
	s_barrier
	s_branch .LBB0_262
.LBB0_262:
	s_add_i32 s100, s16, 0xffff0000
	s_and_b32 s100, s100, 0x10000
	v_add_u32_e32 v0, s100, v175
	v_add3_u32 v212, v0, v176, v177
	v_add3_u32 v0, v0, v178, v177
	ds_read_b128 v[130:133], v212 offset:8192
	ds_read_b128 v[180:183], v0 offset:40960
	ds_read_b128 v[184:187], v0 offset:43008
	ds_read_b128 v[188:191], v0 offset:45056
	ds_read_b128 v[192:195], v0 offset:47104
	ds_read_b128 v[196:199], v0 offset:49152
	ds_read_b128 v[200:203], v0 offset:51200
	ds_read_b128 v[204:207], v0 offset:53248
	ds_read_b128 v[208:211], v0 offset:55296
; #define MFMA16(a, b, c) __builtin_amdgcn_mfma_f32_16x16x32_bf16((a), (b), (c), 0, 0, 0)
; DI void vm_wait0() { asm volatile("s_waitcnt vmcnt(0)" ::: "memory"); }
;   DI unsigned koff(int k) const { return (unsigned)((k >> 6) * EIN + (k & 63)); }
; DI void dma16(const void* g, unsigned char* l) { __builtin_amdgcn_global_load_lds((const unsigned*)g, (lds_u32_t*)(unsigned)(size_t)l, 16, 0, 0); }
; template <class AF, class EF>
; DI void gemm_run(unsigned char* lds, int wv, const AF& af, const bf16_t* __restrict__ Bt, int ldb, int M, int N, int K, const EF& ef, int blk_off) {
;     ...
;     for (int kt = 0; kt < nk; ++kt) {
;       unsigned char* cur = sBase + (kt & 1) * GST;
;       if (kt + 1 < nk) {
;         unsigned char* nxt = sBase + ((kt + 1) & 1) * GST;
;         const int k0 = (kt + 1) << 6;
; #pragma unroll
;         for (int i = 0; i < 4; ++i) {
;           dma16(Ab + aoff[i] + af.koff(k0 + cch), nxt + 32768 + (i * 512 + tid) * 16);
;           dma16(Bt + boff[i] + (unsigned)k0, nxt + (i * 512 + tid) * 16);
;         }
;       }
; #pragma unroll
;       for (int ks = 0; ks < 2; ++ks) {
;         bf16x8 wf[4], xf[8];
; #pragma unroll
;         for (int i = 0; i < 4; ++i) wf[i] = *(const bf16x8*)(cur + (wn * 64 + i * 16 + l15) * 128 + (((ks * 4 + q4) ^ swz) * 16));
; #pragma unroll
;         for (int j = 0; j < 8; ++j) xf[j] = *(const bf16x8*)(cur + 32768 + (wm * 128 + j * 16 + l15) * 128 + (((ks * 4 + q4) ^ swz) * 16));
; #pragma unroll
;         for (int i = 0; i < 4; ++i)
; #pragma unroll
;           for (int j = 0; j < 8; ++j) acc[i][j] = MFMA16(wf[i], xf[j], acc[i][j]);
;       }
;       vm_wait0();
;       __syncthreads();
;     }
.Lmyg261_loop:
	s_waitcnt lgkmcnt(7)
	v_mfma_f32_16x16x32_bf16 v[126:129], v[130:133], v[180:183], v[126:129]
	ds_read_b128 v[226:229], v212 offset:10240
	s_waitcnt lgkmcnt(7)
	v_mfma_f32_16x16x32_bf16 v[118:121], v[130:133], v[184:187], v[118:121]
	s_waitcnt lgkmcnt(6)
	v_mfma_f32_16x16x32_bf16 v[110:113], v[130:133], v[188:191], v[110:113]
	s_waitcnt lgkmcnt(5)
	v_mfma_f32_16x16x32_bf16 v[102:105], v[130:133], v[192:195], v[102:105]
	s_waitcnt lgkmcnt(4)
	v_mfma_f32_16x16x32_bf16 v[94:97], v[130:133], v[196:199], v[94:97]
	s_waitcnt lgkmcnt(3)
	v_mfma_f32_16x16x32_bf16 v[86:89], v[130:133], v[200:203], v[86:89]
	s_waitcnt lgkmcnt(2)
	v_mfma_f32_16x16x32_bf16 v[78:81], v[130:133], v[204:207], v[78:81]
	s_waitcnt lgkmcnt(1)
	v_mfma_f32_16x16x32_bf16 v[70:73], v[130:133], v[208:211], v[70:73]
	s_waitcnt lgkmcnt(0)
	v_mfma_f32_16x16x32_bf16 v[122:125], v[226:229], v[180:183], v[122:125]
	ds_read_b128 v[130:133], v212 offset:12288
	v_mfma_f32_16x16x32_bf16 v[114:117], v[226:229], v[184:187], v[114:117]
	v_mfma_f32_16x16x32_bf16 v[106:109], v[226:229], v[188:191], v[106:109]
	v_mfma_f32_16x16x32_bf16 v[98:101], v[226:229], v[192:195], v[98:101]
	v_mfma_f32_16x16x32_bf16 v[90:93], v[226:229], v[196:199], v[90:93]
	v_mfma_f32_16x16x32_bf16 v[82:85], v[226:229], v[200:203], v[82:85]
	v_mfma_f32_16x16x32_bf16 v[74:77], v[226:229], v[204:207], v[74:77]
	v_mfma_f32_16x16x32_bf16 v[66:69], v[226:229], v[208:211], v[66:69]
	s_waitcnt lgkmcnt(0)
	v_mfma_f32_16x16x32_bf16 v[62:65], v[130:133], v[180:183], v[62:65]
	ds_read_b128 v[226:229], v212 offset:14336
	v_mfma_f32_16x16x32_bf16 v[54:57], v[130:133], v[184:187], v[54:57]
	v_add_u32_e32 v0, s100, v179
	v_mfma_f32_16x16x32_bf16 v[46:49], v[130:133], v[188:191], v[46:49]
	v_add3_u32 v212, v0, v176, v177
	v_mfma_f32_16x16x32_bf16 v[38:41], v[130:133], v[192:195], v[38:41]
	v_add3_u32 v0, v0, v178, v177
	v_mfma_f32_16x16x32_bf16 v[30:33], v[130:133], v[196:199], v[30:33]
	v_mfma_f32_16x16x32_bf16 v[22:25], v[130:133], v[200:203], v[22:25]
	v_mfma_f32_16x16x32_bf16 v[14:17], v[130:133], v[204:207], v[14:17]
	v_mfma_f32_16x16x32_bf16 v[2:5], v[130:133], v[208:211], v[2:5]
	s_waitcnt lgkmcnt(0)
	v_mfma_f32_16x16x32_bf16 v[58:61], v[226:229], v[180:183], v[58:61]
	ds_read_b128 v[130:133], v212 offset:8192
	ds_read_b128 v[180:183], v0 offset:40960
	v_mfma_f32_16x16x32_bf16 v[50:53], v[226:229], v[184:187], v[50:53]
	ds_read_b128 v[184:187], v0 offset:43008
	v_mfma_f32_16x16x32_bf16 v[42:45], v[226:229], v[188:191], v[42:45]
	ds_read_b128 v[188:191], v0 offset:45056
	v_mfma_f32_16x16x32_bf16 v[34:37], v[226:229], v[192:195], v[34:37]
	ds_read_b128 v[192:195], v0 offset:47104
	v_mfma_f32_16x16x32_bf16 v[26:29], v[226:229], v[196:199], v[26:29]
	ds_read_b128 v[196:199], v0 offset:49152
	v_mfma_f32_16x16x32_bf16 v[18:21], v[226:229], v[200:203], v[18:21]
	ds_read_b128 v[200:203], v0 offset:51200
	v_mfma_f32_16x16x32_bf16 v[10:13], v[226:229], v[204:207], v[10:13]
	ds_read_b128 v[204:207], v0 offset:53248
	v_mfma_f32_16x16x32_bf16 v[6:9], v[226:229], v[208:211], v[6:9]
	ds_read_b128 v[208:211], v0 offset:55296
	s_waitcnt lgkmcnt(7)
	v_mfma_f32_16x16x32_bf16 v[126:129], v[130:133], v[180:183], v[126:129]
	ds_read_b128 v[226:229], v212 offset:10240
	s_waitcnt lgkmcnt(7)
	v_mfma_f32_16x16x32_bf16 v[118:121], v[130:133], v[184:187], v[118:121]
	s_waitcnt lgkmcnt(6)
	v_mfma_f32_16x16x32_bf16 v[110:113], v[130:133], v[188:191], v[110:113]
	s_waitcnt lgkmcnt(5)
	v_mfma_f32_16x16x32_bf16 v[102:105], v[130:133], v[192:195], v[102:105]
	s_waitcnt lgkmcnt(4)
	v_mfma_f32_16x16x32_bf16 v[94:97], v[130:133], v[196:199], v[94:97]
	s_waitcnt lgkmcnt(3)
	v_mfma_f32_16x16x32_bf16 v[86:89], v[130:133], v[200:203], v[86:89]
	s_waitcnt lgkmcnt(2)
	v_mfma_f32_16x16x32_bf16 v[78:81], v[130:133], v[204:207], v[78:81]
	s_waitcnt lgkmcnt(1)
	v_mfma_f32_16x16x32_bf16 v[70:73], v[130:133], v[208:211], v[70:73]
	s_waitcnt lgkmcnt(0)
	v_mfma_f32_16x16x32_bf16 v[122:125], v[226:229], v[180:183], v[122:125]
	ds_read_b128 v[130:133], v212 offset:12288
	v_mfma_f32_16x16x32_bf16 v[114:117], v[226:229], v[184:187], v[114:117]
	v_mfma_f32_16x16x32_bf16 v[106:109], v[226:229], v[188:191], v[106:109]
	v_mfma_f32_16x16x32_bf16 v[98:101], v[226:229], v[192:195], v[98:101]
	v_mfma_f32_16x16x32_bf16 v[90:93], v[226:229], v[196:199], v[90:93]
	v_mfma_f32_16x16x32_bf16 v[82:85], v[226:229], v[200:203], v[82:85]
	v_mfma_f32_16x16x32_bf16 v[74:77], v[226:229], v[204:207], v[74:77]
	v_mfma_f32_16x16x32_bf16 v[66:69], v[226:229], v[208:211], v[66:69]
	s_waitcnt lgkmcnt(0)
	v_mfma_f32_16x16x32_bf16 v[62:65], v[130:133], v[180:183], v[62:65]
	ds_read_b128 v[226:229], v212 offset:14336
	v_mfma_f32_16x16x32_bf16 v[54:57], v[130:133], v[184:187], v[54:57]
	v_mfma_f32_16x16x32_bf16 v[46:49], v[130:133], v[188:191], v[46:49]
	v_mfma_f32_16x16x32_bf16 v[38:41], v[130:133], v[192:195], v[38:41]
	v_mfma_f32_16x16x32_bf16 v[30:33], v[130:133], v[196:199], v[30:33]
	v_mfma_f32_16x16x32_bf16 v[22:25], v[130:133], v[200:203], v[22:25]
	v_mfma_f32_16x16x32_bf16 v[14:17], v[130:133], v[204:207], v[14:17]
	v_mfma_f32_16x16x32_bf16 v[2:5], v[130:133], v[208:211], v[2:5]
	s_waitcnt vmcnt(0) lgkmcnt(0)
	s_barrier
	s_add_u32 s4, s4, 0x80
	s_addc_u32 s5, s5, 0
	s_add_i32 s16, s16, 0x10000
	s_cmpk_eq_i32 s4, 0x800
	s_cbranch_scc1 .Lmyg261_tail
	s_add_i32 s100, s16, 0xffff0000
	s_and_b32 s100, s100, 0x10000
	v_add_u32_e32 v0, s100, v175
	v_add3_u32 v212, v0, v176, v177
	v_add3_u32 v0, v0, v178, v177
	s_cmpk_eq_i32 s4, 0x780
	s_cbranch_scc1 .Lmyg261_nodma
	s_setprio 3
	s_and_b32 s17, s16, 0x10000
	s_add_i32 s17, s17, 0
	s_add_i32 s18, s17, 0x2000
	s_add_i32 s17, s17, 0xa000
	v_add_u32_e32 v224, s17, v136
	v_lshl_add_u64 v[222:223], v[160:161], 0, s[4:5]
	v_readfirstlane_b32 s19, v224
	v_add_u32_e32 v224, s18, v136
	s_mov_b32 m0, s19
	v_readfirstlane_b32 s19, v224
	v_add_u32_e32 v224, s17, v138
	global_load_lds_dwordx4 v[222:223], off
	v_lshl_add_u64 v[222:223], v[152:153], 0, s[4:5]
	s_mov_b32 m0, s19
	v_readfirstlane_b32 s19, v224
	v_add_u32_e32 v224, s18, v138
	global_load_lds_dwordx4 v[222:223], off
	v_lshl_add_u64 v[222:223], v[158:159], 0, s[4:5]
	s_mov_b32 m0, s19
	v_readfirstlane_b32 s19, v224
	v_add_u32_e32 v224, s17, v140
	global_load_lds_dwordx4 v[222:223], off
	v_lshl_add_u64 v[222:223], v[150:151], 0, s[4:5]
	s_mov_b32 m0, s19
	v_readfirstlane_b32 s19, v224
	v_add_u32_e32 v224, s18, v140
	global_load_lds_dwordx4 v[222:223], off
	v_lshl_add_u64 v[222:223], v[156:157], 0, s[4:5]
	s_mov_b32 m0, s19
	v_readfirstlane_b32 s19, v224
	v_add_u32_e32 v224, s17, v142
	global_load_lds_dwordx4 v[222:223], off
	v_lshl_add_u64 v[222:223], v[148:149], 0, s[4:5]
	s_mov_b32 m0, s19
	v_readfirstlane_b32 s17, v224
	v_add_u32_e32 v224, s18, v142
	global_load_lds_dwordx4 v[222:223], off
	v_lshl_add_u64 v[222:223], v[154:155], 0, s[4:5]
	s_mov_b32 m0, s17
	v_readfirstlane_b32 s17, v224
	global_load_lds_dwordx4 v[222:223], off
	v_lshl_add_u64 v[222:223], v[146:147], 0, s[4:5]
	s_mov_b32 m0, s17
	s_nop 0
	global_load_lds_dwordx4 v[222:223], off
	s_setprio 0

; DI void vm_wait0() { asm volatile("s_waitcnt vmcnt(0)" ::: "memory"); }
;   DI unsigned rowoff(int m) const { int combo = m >> 9, n = m & 511, b = combo >> 1, g = combo & 1; return (unsigned)((b * SEQ + 16 * n) * EIN + col0 + g * 64); }
;   DI unsigned koff(int k) const { return (unsigned)((k >> 6) * EIN + (k & 63)); }
; DI void dma16(const void* g, unsigned char* l) { __builtin_amdgcn_global_load_lds((const unsigned*)g, (lds_u32_t*)(unsigned)(size_t)l, 16, 0, 0); }
; template <class AF, class EF>
; DI void gemm_run(unsigned char* lds, int wv, const AF& af, const bf16_t* __restrict__ Bt, int ldb, int M, int N, int K, const EF& ef, int blk_off) {
;     ...
;   for (int tile_ = first; tile_ < ntl_eff; tile_ += tstep) {
;     int nt, mt;
;     if (xmap) { nt = tile_ % ntiles; mt = (tile_ / ntiles) * 8 + ((int)blockIdx.x & 7); }
;     else { nt = tile_ % ntiles; mt = tile_ / ntiles; }
;     const int m0 = mt << 8, n0 = nt << 8;
;     f32x4 acc[4][8];
; #pragma unroll
;     for (int i = 0; i < 4; ++i)
; #pragma unroll
;       for (int j = 0; j < 8; ++j) acc[i][j] = (f32x4){0.f, 0.f, 0.f, 0.f};
;     unsigned aoff[4], boff[4];
;     const bf16_t* Ab = af.base();
; #pragma unroll
;     for (int i = 0; i < 4; ++i) {
;       int row = crow + 64 * i;
;       aoff[i] = af.rowoff(m0 + row);
;       int n = n0 + row; n = n < N ? n : N - 1;
;       boff[i] = (unsigned)(n * ldb + cch);
;     }
;     __syncthreads();
; #pragma unroll
;     for (int i = 0; i < 4; ++i) {
;       dma16(Ab + aoff[i] + af.koff(cch), sBase + 32768 + (i * 512 + tid) * 16);
;       dma16(Bt + boff[i], sBase + (i * 512 + tid) * 16);
;     }
;     vm_wait0();
.LBB0_1244:
	s_ashr_i32 s14, s16, 31
	s_lshr_b32 s14, s14, 30
	s_add_i32 s18, s16, s14
	s_ashr_i32 s17, s18, 2
	s_lshl_b32 s14, s17, 3
	s_or_b32 s19, s14, s78
	v_readlane_b32 s14, v254, 34
	v_readlane_b32 s15, v254, 35
	s_and_b64 s[14:15], s[14:15], exec
	s_cselect_b32 s14, s19, s17
	s_lshl_b32 s17, s14, 8
	s_and_b32 s14, s18, 0xfffffc
	s_sub_i32 s14, s16, s14
	s_lshl_b32 s18, s14, 8
	v_add_u32_e32 v3, s18, v168
	v_min_i32_e32 v3, 0x3ff, v3
	v_lshl_or_b32 v6, v3, 10, v145
	v_add_u32_e32 v3, s18, v169
	v_min_i32_e32 v3, 0x3ff, v3
	v_add_u32_e32 v2, s18, v143
	v_lshl_or_b32 v10, v3, 10, v145
	v_add_u32_e32 v3, s18, v170
	v_add_lshl_u32 v0, s17, v143, 10
	v_min_i32_e32 v2, 0x3ff, v2
	v_min_i32_e32 v3, 0x3ff, v3
	v_lshl_or_b32 v2, v2, 10, v145
	v_lshl_or_b32 v14, v3, 10, v145
	v_lshlrev_b64 v[16:17], 1, v[0:1]
	v_readfirstlane_b32 s14, v171
	v_mov_b32_e32 v3, v1
	v_add_lshl_u32 v4, s17, v168, 10
	v_lshl_add_u64 v[18:19], v[138:139], 0, v[16:17]
	s_mov_b32 m0, s14
	v_lshlrev_b64 v[2:3], 1, v[2:3]
	v_readfirstlane_b32 s14, v172
	v_mov_b32_e32 v5, v1
	s_waitcnt lgkmcnt(0)
	s_barrier
	global_load_lds_dwordx4 v[18:19], off
	v_lshl_add_u64 v[18:19], s[4:5], 0, v[2:3]
	s_mov_b32 m0, s14
	v_lshlrev_b64 v[4:5], 1, v[4:5]
	v_readfirstlane_b32 s14, v173
	v_mov_b32_e32 v7, v1
	v_add_lshl_u32 v8, s17, v169, 10
	global_load_lds_dwordx4 v[18:19], off
	v_lshl_add_u64 v[18:19], v[138:139], 0, v[4:5]
	s_mov_b32 m0, s14
	v_lshlrev_b64 v[6:7], 1, v[6:7]
	v_readfirstlane_b32 s14, v174
	v_mov_b32_e32 v9, v1
	global_load_lds_dwordx4 v[18:19], off
	v_lshl_add_u64 v[18:19], s[4:5], 0, v[6:7]
	s_mov_b32 m0, s14
	v_lshlrev_b64 v[8:9], 1, v[8:9]
	v_readfirstlane_b32 s14, v175
	v_mov_b32_e32 v11, v1
	v_add_lshl_u32 v12, s17, v170, 10
	global_load_lds_dwordx4 v[18:19], off
	v_lshl_add_u64 v[18:19], v[138:139], 0, v[8:9]
	s_mov_b32 m0, s14
	v_lshlrev_b64 v[10:11], 1, v[10:11]
	v_readfirstlane_b32 s14, v176
	v_mov_b32_e32 v13, v1
	global_load_lds_dwordx4 v[18:19], off
	v_lshl_add_u64 v[18:19], s[4:5], 0, v[10:11]
	s_mov_b32 m0, s14
	v_lshlrev_b64 v[12:13], 1, v[12:13]
	v_readfirstlane_b32 s14, v177
	v_mov_b32_e32 v15, v1
	global_load_lds_dwordx4 v[18:19], off
	v_lshl_add_u64 v[18:19], v[138:139], 0, v[12:13]
	s_mov_b32 m0, s14
	v_lshlrev_b64 v[14:15], 1, v[14:15]
	v_readfirstlane_b32 s14, v178
	global_load_lds_dwordx4 v[18:19], off
	v_lshl_add_u64 v[18:19], s[4:5], 0, v[14:15]
	s_mov_b32 m0, s14
	v_lshl_add_u64 v[156:157], s[12:13], 0, v[2:3]
	global_load_lds_dwordx4 v[18:19], off
	v_mov_b32_e32 v2, 0
	v_lshl_add_u64 v[150:151], s[12:13], 0, v[14:15]
	v_lshl_add_u64 v[152:153], s[12:13], 0, v[10:11]
	v_lshl_add_u64 v[154:155], s[12:13], 0, v[6:7]
	v_lshl_add_u64 v[158:159], v[148:149], 0, v[12:13]
	v_lshl_add_u64 v[160:161], v[148:149], 0, v[8:9]
	v_lshl_add_u64 v[164:165], v[148:149], 0, v[4:5]
	v_lshl_add_u64 v[166:167], v[148:149], 0, v[16:17]
	s_mov_b32 s19, 0
	s_mov_b64 s[14:15], 0
	s_mov_b32 s20, 0x10000
	v_mov_b32_e32 v3, v2
	v_mov_b32_e32 v4, v2
	v_mov_b32_e32 v5, v2
	v_mov_b32_e32 v6, v2
	v_mov_b32_e32 v7, v2
	v_mov_b32_e32 v8, v2
	v_mov_b32_e32 v9, v2
	v_mov_b32_e32 v10, v2
	v_mov_b32_e32 v11, v2
	v_mov_b32_e32 v12, v2
	v_mov_b32_e32 v13, v2
	v_mov_b32_e32 v14, v2
	v_mov_b32_e32 v15, v2
	v_mov_b32_e32 v16, v2
	v_mov_b32_e32 v17, v2
	v_mov_b32_e32 v30, v2
	v_mov_b32_e32 v31, v2
	v_mov_b32_e32 v32, v2
	v_mov_b32_e32 v33, v2
	v_mov_b32_e32 v42, v2
	v_mov_b32_e32 v43, v2
	v_mov_b32_e32 v44, v2
	v_mov_b32_e32 v45, v2
	v_mov_b32_e32 v50, v2
	v_mov_b32_e32 v51, v2
	v_mov_b32_e32 v52, v2
	v_mov_b32_e32 v53, v2
	v_mov_b32_e32 v58, v2
	v_mov_b32_e32 v59, v2
	v_mov_b32_e32 v60, v2
	v_mov_b32_e32 v61, v2
	v_mov_b32_e32 v66, v2
	v_mov_b32_e32 v67, v2
	v_mov_b32_e32 v68, v2
	v_mov_b32_e32 v69, v2
	v_mov_b32_e32 v74, v2
	v_mov_b32_e32 v75, v2
	v_mov_b32_e32 v76, v2
	v_mov_b32_e32 v77, v2
	v_mov_b32_e32 v82, v2
	v_mov_b32_e32 v83, v2
	v_mov_b32_e32 v84, v2
	v_mov_b32_e32 v85, v2
	v_mov_b32_e32 v90, v2
	v_mov_b32_e32 v91, v2
	v_mov_b32_e32 v92, v2
	v_mov_b32_e32 v93, v2
	v_mov_b32_e32 v98, v2
	v_mov_b32_e32 v99, v2
	v_mov_b32_e32 v100, v2
	v_mov_b32_e32 v101, v2
	v_mov_b32_e32 v106, v2
	v_mov_b32_e32 v107, v2
	v_mov_b32_e32 v108, v2
	v_mov_b32_e32 v109, v2
	v_mov_b32_e32 v114, v2
	v_mov_b32_e32 v115, v2
	v_mov_b32_e32 v116, v2
	v_mov_b32_e32 v117, v2
	v_mov_b32_e32 v122, v2
	v_mov_b32_e32 v123, v2
	v_mov_b32_e32 v124, v2
	v_mov_b32_e32 v125, v2
	v_mov_b32_e32 v70, v2
	v_mov_b32_e32 v71, v2
	v_mov_b32_e32 v72, v2
	v_mov_b32_e32 v73, v2
	v_mov_b32_e32 v78, v2
	v_mov_b32_e32 v79, v2
	v_mov_b32_e32 v80, v2
	v_mov_b32_e32 v81, v2
	v_mov_b32_e32 v86, v2
	v_mov_b32_e32 v87, v2
	v_mov_b32_e32 v88, v2
	v_mov_b32_e32 v89, v2
	v_mov_b32_e32 v94, v2
	v_mov_b32_e32 v95, v2
	v_mov_b32_e32 v96, v2
	v_mov_b32_e32 v97, v2
	v_mov_b32_e32 v102, v2
	v_mov_b32_e32 v103, v2
	v_mov_b32_e32 v104, v2
	v_mov_b32_e32 v105, v2
	v_mov_b32_e32 v110, v2
	v_mov_b32_e32 v111, v2
	v_mov_b32_e32 v112, v2
	v_mov_b32_e32 v113, v2
	v_mov_b32_e32 v118, v2
	v_mov_b32_e32 v119, v2
	v_mov_b32_e32 v120, v2
	v_mov_b32_e32 v121, v2
	v_mov_b32_e32 v126, v2
	v_mov_b32_e32 v127, v2
	v_mov_b32_e32 v128, v2
	v_mov_b32_e32 v129, v2
	v_mov_b32_e32 v62, v2
	v_mov_b32_e32 v63, v2
	v_mov_b32_e32 v64, v2
	v_mov_b32_e32 v65, v2
	v_mov_b32_e32 v54, v2
	v_mov_b32_e32 v55, v2
	v_mov_b32_e32 v56, v2
	v_mov_b32_e32 v57, v2
	v_mov_b32_e32 v46, v2
	v_mov_b32_e32 v47, v2
	v_mov_b32_e32 v48, v2
	v_mov_b32_e32 v49, v2
	v_mov_b32_e32 v38, v2
	v_mov_b32_e32 v39, v2
	v_mov_b32_e32 v40, v2
	v_mov_b32_e32 v41, v2
	v_mov_b32_e32 v26, v2
	v_mov_b32_e32 v27, v2
	v_mov_b32_e32 v28, v2
	v_mov_b32_e32 v29, v2
	v_mov_b32_e32 v22, v2
	v_mov_b32_e32 v23, v2
; #define MFMA16(a, b, c) __builtin_amdgcn_mfma_f32_16x16x32_bf16((a), (b), (c), 0, 0, 0)
; DI void vm_wait0() { asm volatile("s_waitcnt vmcnt(0)" ::: "memory"); }
;   DI unsigned koff(int k) const { return (unsigned)((k >> 6) * EIN + (k & 63)); }
; DI void dma16(const void* g, unsigned char* l) { __builtin_amdgcn_global_load_lds((const unsigned*)g, (lds_u32_t*)(unsigned)(size_t)l, 16, 0, 0); }
; template <class AF, class EF>
; DI void gemm_run(unsigned char* lds, int wv, const AF& af, const bf16_t* __restrict__ Bt, int ldb, int M, int N, int K, const EF& ef, int blk_off) {
;     ...
;     __syncthreads();
; #pragma unroll
;     for (int i = 0; i < 4; ++i) {
;       dma16(Ab + aoff[i] + af.koff(cch), sBase + 32768 + (i * 512 + tid) * 16);
;       dma16(Bt + boff[i], sBase + (i * 512 + tid) * 16);
;     }
;     vm_wait0();
;     __syncthreads();
; #pragma unroll 1
;     for (int kt = 0; kt < nk; ++kt) {
;       unsigned char* cur = sBase + (kt & 1) * GST;
;       if (kt + 1 < nk) {
;         unsigned char* nxt = sBase + ((kt + 1) & 1) * GST;
;         const int k0 = (kt + 1) << 6;
; #pragma unroll
;         for (int i = 0; i < 4; ++i) {
;           dma16(Ab + aoff[i] + af.koff(k0 + cch), nxt + 32768 + (i * 512 + tid) * 16);
;           dma16(Bt + boff[i] + (unsigned)k0, nxt + (i * 512 + tid) * 16);
;         }
;       }
; #pragma unroll
;       for (int ks = 0; ks < 2; ++ks) {
;         bf16x8 wf[4], xf[8];
; #pragma unroll
;         for (int i = 0; i < 4; ++i) wf[i] = *(const bf16x8*)(cur + (wn * 64 + i * 16 + l15) * 128 + (((ks * 4 + q4) ^ swz) * 16));
; #pragma unroll
;         for (int j = 0; j < 8; ++j) xf[j] = *(const bf16x8*)(cur + 32768 + (wm * 128 + j * 16 + l15) * 128 + (((ks * 4 + q4) ^ swz) * 16));
; #pragma unroll
;         for (int i = 0; i < 4; ++i)
; #pragma unroll
;           for (int j = 0; j < 8; ++j) acc[i][j] = MFMA16(wf[i], xf[j], acc[i][j]);
	v_mov_b32_e32 v24, v2
	v_mov_b32_e32 v25, v2
	v_mov_b32_e32 v34, v2
	v_mov_b32_e32 v35, v2
	v_mov_b32_e32 v36, v2
	v_mov_b32_e32 v37, v2
	v_mov_b32_e32 v18, v2
	v_mov_b32_e32 v19, v2
	v_mov_b32_e32 v20, v2
	v_mov_b32_e32 v21, v2
	s_and_b32 s21, s20, 0x10000
	s_add_i32 s21, s21, 0
	s_add_i32 s22, s21, 0x2000
	s_add_i32 s21, s21, 0xa000
	v_add_u32_e32 v224, s21, v140
	v_lshl_add_u64 v[222:223], v[166:167], 0, s[14:15]
	v_readfirstlane_b32 s23, v224
	v_add_u32_e32 v224, s22, v140
	s_mov_b32 m0, s23
	v_readfirstlane_b32 s23, v224
	v_add_u32_e32 v224, s21, v142
	global_load_lds_dwordx4 v[222:223], off
	v_lshl_add_u64 v[222:223], v[156:157], 0, s[14:15]
	s_mov_b32 m0, s23
	v_readfirstlane_b32 s23, v224
	v_add_u32_e32 v224, s22, v142
	global_load_lds_dwordx4 v[222:223], off
	v_lshl_add_u64 v[222:223], v[164:165], 0, s[14:15]
	s_mov_b32 m0, s23
	v_readfirstlane_b32 s23, v224
	v_add_u32_e32 v224, s21, v144
	global_load_lds_dwordx4 v[222:223], off
	v_lshl_add_u64 v[222:223], v[154:155], 0, s[14:15]
	s_mov_b32 m0, s23
	v_readfirstlane_b32 s23, v224
	v_add_u32_e32 v224, s22, v144
	global_load_lds_dwordx4 v[222:223], off
	v_lshl_add_u64 v[222:223], v[160:161], 0, s[14:15]
	s_mov_b32 m0, s23
	v_readfirstlane_b32 s23, v224
	v_add_u32_e32 v224, s21, v146
	global_load_lds_dwordx4 v[222:223], off
	v_lshl_add_u64 v[222:223], v[152:153], 0, s[14:15]
	s_mov_b32 m0, s23
	v_readfirstlane_b32 s21, v224
	v_add_u32_e32 v224, s22, v146
	global_load_lds_dwordx4 v[222:223], off
	v_lshl_add_u64 v[222:223], v[158:159], 0, s[14:15]
	s_mov_b32 m0, s21
	v_readfirstlane_b32 s21, v224
	global_load_lds_dwordx4 v[222:223], off
	v_lshl_add_u64 v[222:223], v[150:151], 0, s[14:15]
	s_mov_b32 m0, s21
	s_nop 0
	global_load_lds_dwordx4 v[222:223], off
	s_waitcnt vmcnt(8) lgkmcnt(0)
	s_barrier
	s_branch .LBB0_1246
.LBB0_1246:
	s_add_i32 s100, s20, 0xffff0000
	s_and_b32 s100, s100, 0x10000
	v_add_u32_e32 v0, s100, v179
	v_add3_u32 v212, v0, v180, v181
	v_add3_u32 v0, v0, v182, v181
	ds_read_b128 v[130:133], v212 offset:8192
	ds_read_b128 v[184:187], v0 offset:43008
	ds_read_b128 v[134:137], v0 offset:40960
	ds_read_b128 v[188:191], v0 offset:45056
	ds_read_b128 v[192:195], v0 offset:47104
	ds_read_b128 v[196:199], v0 offset:49152
	ds_read_b128 v[200:203], v0 offset:51200
	ds_read_b128 v[204:207], v0 offset:53248
	ds_read_b128 v[208:211], v0 offset:55296
.Lmyg1245_loop:
	s_waitcnt lgkmcnt(7)
	v_mfma_f32_16x16x32_bf16 v[118:121], v[130:133], v[184:187], v[118:121]
	ds_read_b128 v[226:229], v212 offset:10240
	s_waitcnt lgkmcnt(7)
	v_mfma_f32_16x16x32_bf16 v[126:129], v[130:133], v[134:137], v[126:129]
	s_waitcnt lgkmcnt(6)
	v_mfma_f32_16x16x32_bf16 v[110:113], v[130:133], v[188:191], v[110:113]
	s_waitcnt lgkmcnt(5)
	v_mfma_f32_16x16x32_bf16 v[102:105], v[130:133], v[192:195], v[102:105]
	s_waitcnt lgkmcnt(4)
	v_mfma_f32_16x16x32_bf16 v[94:97], v[130:133], v[196:199], v[94:97]
	s_waitcnt lgkmcnt(3)
	v_mfma_f32_16x16x32_bf16 v[86:89], v[130:133], v[200:203], v[86:89]
	s_waitcnt lgkmcnt(2)
	v_mfma_f32_16x16x32_bf16 v[78:81], v[130:133], v[204:207], v[78:81]
	s_waitcnt lgkmcnt(1)
	v_mfma_f32_16x16x32_bf16 v[70:73], v[130:133], v[208:211], v[70:73]
	s_waitcnt lgkmcnt(0)
	v_mfma_f32_16x16x32_bf16 v[122:125], v[226:229], v[134:137], v[122:125]
	ds_read_b128 v[130:133], v212 offset:12288
	v_mfma_f32_16x16x32_bf16 v[114:117], v[226:229], v[184:187], v[114:117]
	v_mfma_f32_16x16x32_bf16 v[106:109], v[226:229], v[188:191], v[106:109]
	v_mfma_f32_16x16x32_bf16 v[98:101], v[226:229], v[192:195], v[98:101]
	v_mfma_f32_16x16x32_bf16 v[90:93], v[226:229], v[196:199], v[90:93]
	v_mfma_f32_16x16x32_bf16 v[82:85], v[226:229], v[200:203], v[82:85]
	v_mfma_f32_16x16x32_bf16 v[74:77], v[226:229], v[204:207], v[74:77]
	v_mfma_f32_16x16x32_bf16 v[66:69], v[226:229], v[208:211], v[66:69]
	s_waitcnt lgkmcnt(0)
	v_mfma_f32_16x16x32_bf16 v[58:61], v[130:133], v[134:137], v[58:61]
	ds_read_b128 v[226:229], v212 offset:14336
	v_mfma_f32_16x16x32_bf16 v[50:53], v[130:133], v[184:187], v[50:53]
	v_add_u32_e32 v0, s100, v183
	v_mfma_f32_16x16x32_bf16 v[42:45], v[130:133], v[188:191], v[42:45]
	v_add3_u32 v212, v0, v180, v181
	v_mfma_f32_16x16x32_bf16 v[30:33], v[130:133], v[192:195], v[30:33]
	v_add3_u32 v0, v0, v182, v181
	v_mfma_f32_16x16x32_bf16 v[14:17], v[130:133], v[196:199], v[14:17]
	v_mfma_f32_16x16x32_bf16 v[10:13], v[130:133], v[200:203], v[10:13]
	v_mfma_f32_16x16x32_bf16 v[6:9], v[130:133], v[204:207], v[6:9]
	v_mfma_f32_16x16x32_bf16 v[2:5], v[130:133], v[208:211], v[2:5]
	s_waitcnt lgkmcnt(0)
; #define MFMA16(a, b, c) __builtin_amdgcn_mfma_f32_16x16x32_bf16((a), (b), (c), 0, 0, 0)
; DI void vm_wait0() { asm volatile("s_waitcnt vmcnt(0)" ::: "memory"); }
;   DI unsigned koff(int k) const { return (unsigned)((k >> 6) * EIN + (k & 63)); }
; DI void dma16(const void* g, unsigned char* l) { __builtin_amdgcn_global_load_lds((const unsigned*)g, (lds_u32_t*)(unsigned)(size_t)l, 16, 0, 0); }
; template <class AF, class EF>
; DI void gemm_run(unsigned char* lds, int wv, const AF& af, const bf16_t* __restrict__ Bt, int ldb, int M, int N, int K, const EF& ef, int blk_off) {
;     ...
;     for (int kt = 0; kt < nk; ++kt) {
;       unsigned char* cur = sBase + (kt & 1) * GST;
;       if (kt + 1 < nk) {
;         unsigned char* nxt = sBase + ((kt + 1) & 1) * GST;
;         const int k0 = (kt + 1) << 6;
; #pragma unroll
;         for (int i = 0; i < 4; ++i) {
;           dma16(Ab + aoff[i] + af.koff(k0 + cch), nxt + 32768 + (i * 512 + tid) * 16);
;           dma16(Bt + boff[i] + (unsigned)k0, nxt + (i * 512 + tid) * 16);
;         }
;       }
; #pragma unroll
;       for (int ks = 0; ks < 2; ++ks) {
;         bf16x8 wf[4], xf[8];
; #pragma unroll
;         for (int i = 0; i < 4; ++i) wf[i] = *(const bf16x8*)(cur + (wn * 64 + i * 16 + l15) * 128 + (((ks * 4 + q4) ^ swz) * 16));
; #pragma unroll
;         for (int j = 0; j < 8; ++j) xf[j] = *(const bf16x8*)(cur + 32768 + (wm * 128 + j * 16 + l15) * 128 + (((ks * 4 + q4) ^ swz) * 16));
; #pragma unroll
;         for (int i = 0; i < 4; ++i)
; #pragma unroll
;           for (int j = 0; j < 8; ++j) acc[i][j] = MFMA16(wf[i], xf[j], acc[i][j]);
;       }
;       vm_wait0();
;       __syncthreads();
;     }
	v_mfma_f32_16x16x32_bf16 v[54:57], v[226:229], v[184:187], v[54:57]
	ds_read_b128 v[130:133], v212 offset:8192
	ds_read_b128 v[184:187], v0 offset:43008
	v_mfma_f32_16x16x32_bf16 v[62:65], v[226:229], v[134:137], v[62:65]
	ds_read_b128 v[134:137], v0 offset:40960
	v_mfma_f32_16x16x32_bf16 v[46:49], v[226:229], v[188:191], v[46:49]
	ds_read_b128 v[188:191], v0 offset:45056
	v_mfma_f32_16x16x32_bf16 v[38:41], v[226:229], v[192:195], v[38:41]
	ds_read_b128 v[192:195], v0 offset:47104
	v_mfma_f32_16x16x32_bf16 v[26:29], v[226:229], v[196:199], v[26:29]
	ds_read_b128 v[196:199], v0 offset:49152
	v_mfma_f32_16x16x32_bf16 v[22:25], v[226:229], v[200:203], v[22:25]
	ds_read_b128 v[200:203], v0 offset:51200
	v_mfma_f32_16x16x32_bf16 v[34:37], v[226:229], v[204:207], v[34:37]
	ds_read_b128 v[204:207], v0 offset:53248
	v_mfma_f32_16x16x32_bf16 v[18:21], v[226:229], v[208:211], v[18:21]
	ds_read_b128 v[208:211], v0 offset:55296
	s_waitcnt lgkmcnt(7)
	v_mfma_f32_16x16x32_bf16 v[118:121], v[130:133], v[184:187], v[118:121]
	ds_read_b128 v[226:229], v212 offset:10240
	s_waitcnt lgkmcnt(7)
	v_mfma_f32_16x16x32_bf16 v[126:129], v[130:133], v[134:137], v[126:129]
	s_waitcnt lgkmcnt(6)
	v_mfma_f32_16x16x32_bf16 v[110:113], v[130:133], v[188:191], v[110:113]
	s_waitcnt lgkmcnt(5)
	v_mfma_f32_16x16x32_bf16 v[102:105], v[130:133], v[192:195], v[102:105]
	s_waitcnt lgkmcnt(4)
	v_mfma_f32_16x16x32_bf16 v[94:97], v[130:133], v[196:199], v[94:97]
	s_waitcnt lgkmcnt(3)
	v_mfma_f32_16x16x32_bf16 v[86:89], v[130:133], v[200:203], v[86:89]
	s_waitcnt lgkmcnt(2)
	v_mfma_f32_16x16x32_bf16 v[78:81], v[130:133], v[204:207], v[78:81]
	s_waitcnt lgkmcnt(1)
	v_mfma_f32_16x16x32_bf16 v[70:73], v[130:133], v[208:211], v[70:73]
	s_waitcnt lgkmcnt(0)
	v_mfma_f32_16x16x32_bf16 v[122:125], v[226:229], v[134:137], v[122:125]
	ds_read_b128 v[130:133], v212 offset:12288
	v_mfma_f32_16x16x32_bf16 v[114:117], v[226:229], v[184:187], v[114:117]
	v_mfma_f32_16x16x32_bf16 v[106:109], v[226:229], v[188:191], v[106:109]
	v_mfma_f32_16x16x32_bf16 v[98:101], v[226:229], v[192:195], v[98:101]
	v_mfma_f32_16x16x32_bf16 v[90:93], v[226:229], v[196:199], v[90:93]
	v_mfma_f32_16x16x32_bf16 v[82:85], v[226:229], v[200:203], v[82:85]
	v_mfma_f32_16x16x32_bf16 v[74:77], v[226:229], v[204:207], v[74:77]
	v_mfma_f32_16x16x32_bf16 v[66:69], v[226:229], v[208:211], v[66:69]
	s_waitcnt lgkmcnt(0)
	v_mfma_f32_16x16x32_bf16 v[58:61], v[130:133], v[134:137], v[58:61]
	ds_read_b128 v[226:229], v212 offset:14336
	v_mfma_f32_16x16x32_bf16 v[50:53], v[130:133], v[184:187], v[50:53]
	v_mfma_f32_16x16x32_bf16 v[42:45], v[130:133], v[188:191], v[42:45]
	v_mfma_f32_16x16x32_bf16 v[30:33], v[130:133], v[192:195], v[30:33]
	v_mfma_f32_16x16x32_bf16 v[14:17], v[130:133], v[196:199], v[14:17]
	v_mfma_f32_16x16x32_bf16 v[10:13], v[130:133], v[200:203], v[10:13]
	v_mfma_f32_16x16x32_bf16 v[6:9], v[130:133], v[204:207], v[6:9]
	v_mfma_f32_16x16x32_bf16 v[2:5], v[130:133], v[208:211], v[2:5]
	s_waitcnt vmcnt(0) lgkmcnt(0)
	s_barrier
	s_add_u32 s14, s14, 0x80
	s_addc_u32 s15, s15, 0
	s_add_i32 s20, s20, 0x10000
	s_add_i32 s19, s19, 1
	s_cmpk_eq_i32 s14, 0x800
	s_cbranch_scc1 .Lmyg1245_tail
	s_add_i32 s100, s20, 0xffff0000
	s_and_b32 s100, s100, 0x10000
	v_add_u32_e32 v0, s100, v179
	v_add3_u32 v212, v0, v180, v181
	v_add3_u32 v0, v0, v182, v181
	s_cmp_gt_u32 s19, 14
	s_cbranch_scc1 .Lmyg1245_nodma
	s_setprio 3
	s_and_b32 s21, s20, 0x10000
	s_add_i32 s21, s21, 0
	s_add_i32 s22, s21, 0x2000
	s_add_i32 s21, s21, 0xa000
	v_add_u32_e32 v224, s21, v140
	v_lshl_add_u64 v[222:223], v[166:167], 0, s[14:15]
	v_readfirstlane_b32 s23, v224
	v_add_u32_e32 v224, s22, v140
	s_mov_b32 m0, s23
	v_readfirstlane_b32 s23, v224
	v_add_u32_e32 v224, s21, v142
	global_load_lds_dwordx4 v[222:223], off
	v_lshl_add_u64 v[222:223], v[156:157], 0, s[14:15]
	s_mov_b32 m0, s23
	v_readfirstlane_b32 s23, v224
	v_add_u32_e32 v224, s22, v142
	global_load_lds_dwordx4 v[222:223], off
	v_lshl_add_u64 v[222:223], v[164:165], 0, s[14:15]
	s_mov_b32 m0, s23
	v_readfirstlane_b32 s23, v224
	v_add_u32_e32 v224, s21, v144
	global_load_lds_dwordx4 v[222:223], off
	v_lshl_add_u64 v[222:223], v[154:155], 0, s[14:15]
	s_mov_b32 m0, s23
	v_readfirstlane_b32 s23, v224
	v_add_u32_e32 v224, s22, v144
	global_load_lds_dwordx4 v[222:223], off
	v_lshl_add_u64 v[222:223], v[160:161], 0, s[14:15]
	s_mov_b32 m0, s23
	v_readfirstlane_b32 s23, v224
	v_add_u32_e32 v224, s21, v146
	global_load_lds_dwordx4 v[222:223], off
	v_lshl_add_u64 v[222:223], v[152:153], 0, s[14:15]
	s_mov_b32 m0, s23
	v_readfirstlane_b32 s21, v224
	v_add_u32_e32 v224, s22, v146
	global_load_lds_dwordx4 v[222:223], off
	v_lshl_add_u64 v[222:223], v[158:159], 0, s[14:15]
	s_mov_b32 m0, s21
	v_readfirstlane_b32 s21, v224
	global_load_lds_dwordx4 v[222:223], off
	v_lshl_add_u64 v[222:223], v[150:151], 0, s[14:15]
	s_mov_b32 m0, s21
	s_nop 0
	global_load_lds_dwordx4 v[222:223], off
	s_setprio 0

; DI void vm_wait0() { asm volatile("s_waitcnt vmcnt(0)" ::: "memory"); }
;   DI unsigned rowoff(int m) const { int combo = m >> 9, n = m & 511, b = combo >> 1, g = combo & 1; return (unsigned)((b * SEQ + 16 * n) * EIN + col0 + g * 64); }
;   DI unsigned koff(int k) const { return (unsigned)((k >> 6) * EIN + (k & 63)); }
; DI void dma16(const void* g, unsigned char* l) { __builtin_amdgcn_global_load_lds((const unsigned*)g, (lds_u32_t*)(unsigned)(size_t)l, 16, 0, 0); }
; template <class AF, class EF>
; DI void gemm_run(unsigned char* lds, int wv, const AF& af, const bf16_t* __restrict__ Bt, int ldb, int M, int N, int K, const EF& ef, int blk_off) {
;     ...
;   for (int tile_ = first; tile_ < ntl_eff; tile_ += tstep) {
;     int nt, mt;
;     if (xmap) { nt = tile_ % ntiles; mt = (tile_ / ntiles) * 8 + ((int)blockIdx.x & 7); }
;     else { nt = tile_ % ntiles; mt = tile_ / ntiles; }
;     const int m0 = mt << 8, n0 = nt << 8;
;     f32x4 acc[4][8];
; #pragma unroll
;     for (int i = 0; i < 4; ++i)
; #pragma unroll
;       for (int j = 0; j < 8; ++j) acc[i][j] = (f32x4){0.f, 0.f, 0.f, 0.f};
;     unsigned aoff[4], boff[4];
;     const bf16_t* Ab = af.base();
; #pragma unroll
;     for (int i = 0; i < 4; ++i) {
;       int row = crow + 64 * i;
;       aoff[i] = af.rowoff(m0 + row);
;       int n = n0 + row; n = n < N ? n : N - 1;
;       boff[i] = (unsigned)(n * ldb + cch);
;     }
;     __syncthreads();
; #pragma unroll
;     for (int i = 0; i < 4; ++i) {
;       dma16(Ab + aoff[i] + af.koff(cch), sBase + 32768 + (i * 512 + tid) * 16);
;       dma16(Bt + boff[i], sBase + (i * 512 + tid) * 16);
;     }
;     vm_wait0();
.LBB0_1266:
	s_ashr_i32 s10, s12, 31
	s_lshr_b32 s10, s10, 28
	s_add_i32 s14, s12, s10
	s_ashr_i32 s13, s14, 4
	s_lshl_b32 s10, s13, 3
	s_or_b32 s15, s10, s78
	v_readlane_b32 s10, v254, 34
	v_readlane_b32 s11, v254, 35
	s_and_b64 s[10:11], s[10:11], exec
	s_cselect_b32 s10, s15, s13
	s_lshl_b32 s13, s10, 8
	s_and_b32 s10, s14, 0xfffff0
	s_sub_i32 s10, s12, s10
	s_lshl_b32 s14, s10, 8
	v_add_u32_e32 v3, s14, v163
	v_min_i32_e32 v3, 0xfff, v3
	v_lshl_or_b32 v6, v3, 10, v139
	v_add_u32_e32 v3, s14, v164
	v_min_i32_e32 v3, 0xfff, v3
	v_add_u32_e32 v2, s14, v137
	v_lshl_or_b32 v10, v3, 10, v139
	v_add_u32_e32 v3, s14, v165
	v_add_lshl_u32 v0, s13, v137, 10
	v_min_i32_e32 v2, 0xfff, v2
	v_min_i32_e32 v3, 0xfff, v3
	v_lshl_or_b32 v2, v2, 10, v139
	v_lshl_or_b32 v14, v3, 10, v139
	v_lshlrev_b64 v[16:17], 1, v[0:1]
	v_readfirstlane_b32 s10, v166
	v_mov_b32_e32 v3, v1
	v_add_lshl_u32 v4, s13, v163, 10
	v_lshl_add_u64 v[18:19], v[134:135], 0, v[16:17]
	s_mov_b32 m0, s10
	v_lshlrev_b64 v[2:3], 1, v[2:3]
	v_readfirstlane_b32 s10, v167
	v_mov_b32_e32 v5, v1
	s_barrier
	global_load_lds_dwordx4 v[18:19], off
	v_lshl_add_u64 v[18:19], s[4:5], 0, v[2:3]
	s_mov_b32 m0, s10
	v_lshlrev_b64 v[4:5], 1, v[4:5]
	v_readfirstlane_b32 s10, v168
	v_mov_b32_e32 v7, v1
	v_add_lshl_u32 v8, s13, v164, 10
	global_load_lds_dwordx4 v[18:19], off
	v_lshl_add_u64 v[18:19], v[134:135], 0, v[4:5]
	s_mov_b32 m0, s10
	v_lshlrev_b64 v[6:7], 1, v[6:7]
	v_readfirstlane_b32 s10, v169
	v_mov_b32_e32 v9, v1
	global_load_lds_dwordx4 v[18:19], off
	v_lshl_add_u64 v[18:19], s[4:5], 0, v[6:7]
	s_mov_b32 m0, s10
	v_lshlrev_b64 v[8:9], 1, v[8:9]
	v_readfirstlane_b32 s10, v170
	v_mov_b32_e32 v11, v1
	v_add_lshl_u32 v12, s13, v165, 10
	global_load_lds_dwordx4 v[18:19], off
	v_lshl_add_u64 v[18:19], v[134:135], 0, v[8:9]
	s_mov_b32 m0, s10
	v_lshlrev_b64 v[10:11], 1, v[10:11]
	v_readfirstlane_b32 s10, v171
	v_mov_b32_e32 v13, v1
	global_load_lds_dwordx4 v[18:19], off
	v_lshl_add_u64 v[18:19], s[4:5], 0, v[10:11]
	s_mov_b32 m0, s10
	v_lshlrev_b64 v[12:13], 1, v[12:13]
	v_readfirstlane_b32 s10, v172
	v_mov_b32_e32 v15, v1
	global_load_lds_dwordx4 v[18:19], off
	v_lshl_add_u64 v[18:19], v[134:135], 0, v[12:13]
	s_mov_b32 m0, s10
	v_lshlrev_b64 v[14:15], 1, v[14:15]
	v_readfirstlane_b32 s10, v173
	global_load_lds_dwordx4 v[18:19], off
	v_lshl_add_u64 v[18:19], s[4:5], 0, v[14:15]
	s_mov_b32 m0, s10
	v_lshl_add_u64 v[152:153], s[8:9], 0, v[2:3]
	global_load_lds_dwordx4 v[18:19], off
	v_mov_b32_e32 v2, 0
	v_lshl_add_u64 v[146:147], s[8:9], 0, v[14:15]
	v_lshl_add_u64 v[148:149], s[8:9], 0, v[10:11]
	v_lshl_add_u64 v[150:151], s[8:9], 0, v[6:7]
	v_lshl_add_u64 v[154:155], v[144:145], 0, v[12:13]
	v_lshl_add_u64 v[156:157], v[144:145], 0, v[8:9]
	v_lshl_add_u64 v[158:159], v[144:145], 0, v[4:5]
	v_lshl_add_u64 v[160:161], v[144:145], 0, v[16:17]
	s_mov_b64 s[10:11], 0
	s_mov_b32 s15, 0x10000
	v_mov_b32_e32 v3, v2
	v_mov_b32_e32 v4, v2
	v_mov_b32_e32 v5, v2
	v_mov_b32_e32 v6, v2
	v_mov_b32_e32 v7, v2
	v_mov_b32_e32 v8, v2
	v_mov_b32_e32 v9, v2
	v_mov_b32_e32 v10, v2
	v_mov_b32_e32 v11, v2
	v_mov_b32_e32 v12, v2
	v_mov_b32_e32 v13, v2
	v_mov_b32_e32 v14, v2
	v_mov_b32_e32 v15, v2
	v_mov_b32_e32 v16, v2
	v_mov_b32_e32 v17, v2
	v_mov_b32_e32 v26, v2
	v_mov_b32_e32 v27, v2
	v_mov_b32_e32 v28, v2
	v_mov_b32_e32 v29, v2
	v_mov_b32_e32 v38, v2
	v_mov_b32_e32 v39, v2
	v_mov_b32_e32 v40, v2
	v_mov_b32_e32 v41, v2
	v_mov_b32_e32 v46, v2
	v_mov_b32_e32 v47, v2
	v_mov_b32_e32 v48, v2
	v_mov_b32_e32 v49, v2
	v_mov_b32_e32 v54, v2
	v_mov_b32_e32 v55, v2
	v_mov_b32_e32 v56, v2
	v_mov_b32_e32 v57, v2
	v_mov_b32_e32 v62, v2
	v_mov_b32_e32 v63, v2
	v_mov_b32_e32 v64, v2
	v_mov_b32_e32 v65, v2
	v_mov_b32_e32 v74, v2
	v_mov_b32_e32 v75, v2
	v_mov_b32_e32 v76, v2
	v_mov_b32_e32 v77, v2
	v_mov_b32_e32 v82, v2
	v_mov_b32_e32 v83, v2
	v_mov_b32_e32 v84, v2
	v_mov_b32_e32 v85, v2
	v_mov_b32_e32 v90, v2
	v_mov_b32_e32 v91, v2
	v_mov_b32_e32 v92, v2
	v_mov_b32_e32 v93, v2
	v_mov_b32_e32 v98, v2
	v_mov_b32_e32 v99, v2
	v_mov_b32_e32 v100, v2
	v_mov_b32_e32 v101, v2
	v_mov_b32_e32 v106, v2
	v_mov_b32_e32 v107, v2
	v_mov_b32_e32 v108, v2
	v_mov_b32_e32 v109, v2
	v_mov_b32_e32 v114, v2
	v_mov_b32_e32 v115, v2
	v_mov_b32_e32 v116, v2
	v_mov_b32_e32 v117, v2
	v_mov_b32_e32 v122, v2
	v_mov_b32_e32 v123, v2
	v_mov_b32_e32 v124, v2
	v_mov_b32_e32 v125, v2
	v_mov_b32_e32 v70, v2
	v_mov_b32_e32 v71, v2
	v_mov_b32_e32 v72, v2
	v_mov_b32_e32 v73, v2
	v_mov_b32_e32 v78, v2
	v_mov_b32_e32 v79, v2
	v_mov_b32_e32 v80, v2
	v_mov_b32_e32 v81, v2
	v_mov_b32_e32 v86, v2
	v_mov_b32_e32 v87, v2
	v_mov_b32_e32 v88, v2
	v_mov_b32_e32 v89, v2
	v_mov_b32_e32 v94, v2
	v_mov_b32_e32 v95, v2
	v_mov_b32_e32 v96, v2
	v_mov_b32_e32 v97, v2
	v_mov_b32_e32 v102, v2
	v_mov_b32_e32 v103, v2
	v_mov_b32_e32 v104, v2
	v_mov_b32_e32 v105, v2
	v_mov_b32_e32 v110, v2
	v_mov_b32_e32 v111, v2
	v_mov_b32_e32 v112, v2
	v_mov_b32_e32 v113, v2
	v_mov_b32_e32 v118, v2
	v_mov_b32_e32 v119, v2
	v_mov_b32_e32 v120, v2
	v_mov_b32_e32 v121, v2
	v_mov_b32_e32 v126, v2
	v_mov_b32_e32 v127, v2
	v_mov_b32_e32 v128, v2
	v_mov_b32_e32 v129, v2
	v_mov_b32_e32 v66, v2
	v_mov_b32_e32 v67, v2
	v_mov_b32_e32 v68, v2
	v_mov_b32_e32 v69, v2
	v_mov_b32_e32 v58, v2
	v_mov_b32_e32 v59, v2
	v_mov_b32_e32 v60, v2
	v_mov_b32_e32 v61, v2
	v_mov_b32_e32 v50, v2
	v_mov_b32_e32 v51, v2
	v_mov_b32_e32 v52, v2
	v_mov_b32_e32 v53, v2
	v_mov_b32_e32 v42, v2
	v_mov_b32_e32 v43, v2
	v_mov_b32_e32 v44, v2
	v_mov_b32_e32 v45, v2
	v_mov_b32_e32 v30, v2
	v_mov_b32_e32 v31, v2
	v_mov_b32_e32 v32, v2
	v_mov_b32_e32 v33, v2
	v_mov_b32_e32 v22, v2
	v_mov_b32_e32 v23, v2
	v_mov_b32_e32 v24, v2
	v_mov_b32_e32 v25, v2
; #define MFMA16(a, b, c) __builtin_amdgcn_mfma_f32_16x16x32_bf16((a), (b), (c), 0, 0, 0)
; DI void vm_wait0() { asm volatile("s_waitcnt vmcnt(0)" ::: "memory"); }
;   DI unsigned koff(int k) const { return (unsigned)((k >> 6) * EIN + (k & 63)); }
; DI void dma16(const void* g, unsigned char* l) { __builtin_amdgcn_global_load_lds((const unsigned*)g, (lds_u32_t*)(unsigned)(size_t)l, 16, 0, 0); }
; template <class AF, class EF>
; DI void gemm_run(unsigned char* lds, int wv, const AF& af, const bf16_t* __restrict__ Bt, int ldb, int M, int N, int K, const EF& ef, int blk_off) {
;     ...
;     __syncthreads();
; #pragma unroll
;     for (int i = 0; i < 4; ++i) {
;       dma16(Ab + aoff[i] + af.koff(cch), sBase + 32768 + (i * 512 + tid) * 16);
;       dma16(Bt + boff[i], sBase + (i * 512 + tid) * 16);
;     }
;     vm_wait0();
;     __syncthreads();
; #pragma unroll 1
;     for (int kt = 0; kt < nk; ++kt) {
;       unsigned char* cur = sBase + (kt & 1) * GST;
;       if (kt + 1 < nk) {
;         unsigned char* nxt = sBase + ((kt + 1) & 1) * GST;
;         const int k0 = (kt + 1) << 6;
; #pragma unroll
;         for (int i = 0; i < 4; ++i) {
;           dma16(Ab + aoff[i] + af.koff(k0 + cch), nxt + 32768 + (i * 512 + tid) * 16);
;           dma16(Bt + boff[i] + (unsigned)k0, nxt + (i * 512 + tid) * 16);
;         }
;       }
; #pragma unroll
;       for (int ks = 0; ks < 2; ++ks) {
;         bf16x8 wf[4], xf[8];
; #pragma unroll
;         for (int i = 0; i < 4; ++i) wf[i] = *(const bf16x8*)(cur + (wn * 64 + i * 16 + l15) * 128 + (((ks * 4 + q4) ^ swz) * 16));
; #pragma unroll
;         for (int j = 0; j < 8; ++j) xf[j] = *(const bf16x8*)(cur + 32768 + (wm * 128 + j * 16 + l15) * 128 + (((ks * 4 + q4) ^ swz) * 16));
; #pragma unroll
;         for (int i = 0; i < 4; ++i)
; #pragma unroll
;           for (int j = 0; j < 8; ++j) acc[i][j] = MFMA16(wf[i], xf[j], acc[i][j]);
	v_mov_b32_e32 v18, v2
	v_mov_b32_e32 v19, v2
	v_mov_b32_e32 v20, v2
	v_mov_b32_e32 v21, v2
	v_mov_b32_e32 v34, v2
	v_mov_b32_e32 v35, v2
	v_mov_b32_e32 v36, v2
	v_mov_b32_e32 v37, v2
	s_and_b32 s16, s15, 0x10000
	s_add_i32 s16, s16, 0
	s_add_i32 s17, s16, 0x2000
	s_add_i32 s16, s16, 0xa000
	v_add_u32_e32 v224, s16, v136
	v_lshl_add_u64 v[222:223], v[160:161], 0, s[10:11]
	v_readfirstlane_b32 s18, v224
	v_add_u32_e32 v224, s17, v136
	s_mov_b32 m0, s18
	v_readfirstlane_b32 s18, v224
	v_add_u32_e32 v224, s16, v138
	global_load_lds_dwordx4 v[222:223], off
	v_lshl_add_u64 v[222:223], v[152:153], 0, s[10:11]
	s_mov_b32 m0, s18
	v_readfirstlane_b32 s18, v224
	v_add_u32_e32 v224, s17, v138
	global_load_lds_dwordx4 v[222:223], off
	v_lshl_add_u64 v[222:223], v[158:159], 0, s[10:11]
	s_mov_b32 m0, s18
	v_readfirstlane_b32 s18, v224
	v_add_u32_e32 v224, s16, v140
	global_load_lds_dwordx4 v[222:223], off
	v_lshl_add_u64 v[222:223], v[150:151], 0, s[10:11]
	s_mov_b32 m0, s18
	v_readfirstlane_b32 s18, v224
	v_add_u32_e32 v224, s17, v140
	global_load_lds_dwordx4 v[222:223], off
	v_lshl_add_u64 v[222:223], v[156:157], 0, s[10:11]
	s_mov_b32 m0, s18
	v_readfirstlane_b32 s18, v224
	v_add_u32_e32 v224, s16, v142
	global_load_lds_dwordx4 v[222:223], off
	v_lshl_add_u64 v[222:223], v[148:149], 0, s[10:11]
	s_mov_b32 m0, s18
	v_readfirstlane_b32 s16, v224
	v_add_u32_e32 v224, s17, v142
	global_load_lds_dwordx4 v[222:223], off
	v_lshl_add_u64 v[222:223], v[154:155], 0, s[10:11]
	s_mov_b32 m0, s16
	v_readfirstlane_b32 s16, v224
	global_load_lds_dwordx4 v[222:223], off
	v_lshl_add_u64 v[222:223], v[146:147], 0, s[10:11]
	s_mov_b32 m0, s16
	s_nop 0
	global_load_lds_dwordx4 v[222:223], off
	s_waitcnt vmcnt(8) lgkmcnt(0)
	s_barrier
	s_branch .LBB0_1268
.LBB0_1268:
	s_add_i32 s100, s15, 0xffff0000
	s_and_b32 s100, s100, 0x10000
	v_add_u32_e32 v0, s100, v174
	v_add3_u32 v179, v0, v175, v176
	v_add3_u32 v0, v0, v177, v176
	ds_read_b128 v[130:133], v179 offset:8192
	ds_read_b128 v[180:183], v0 offset:40960
	ds_read_b128 v[184:187], v0 offset:43008
	ds_read_b128 v[188:191], v0 offset:45056
	ds_read_b128 v[192:195], v0 offset:47104
	ds_read_b128 v[196:199], v0 offset:49152
	ds_read_b128 v[200:203], v0 offset:51200
	ds_read_b128 v[204:207], v0 offset:53248
	ds_read_b128 v[208:211], v0 offset:55296
.Lmyg1267_loop:
	s_waitcnt lgkmcnt(7)
	v_mfma_f32_16x16x32_bf16 v[126:129], v[130:133], v[180:183], v[126:129]
	ds_read_b128 v[226:229], v179 offset:10240
	s_waitcnt lgkmcnt(7)
	v_mfma_f32_16x16x32_bf16 v[118:121], v[130:133], v[184:187], v[118:121]
	s_waitcnt lgkmcnt(6)
	v_mfma_f32_16x16x32_bf16 v[110:113], v[130:133], v[188:191], v[110:113]
	s_waitcnt lgkmcnt(5)
	v_mfma_f32_16x16x32_bf16 v[102:105], v[130:133], v[192:195], v[102:105]
	s_waitcnt lgkmcnt(4)
	v_mfma_f32_16x16x32_bf16 v[94:97], v[130:133], v[196:199], v[94:97]
	s_waitcnt lgkmcnt(3)
	v_mfma_f32_16x16x32_bf16 v[86:89], v[130:133], v[200:203], v[86:89]
	s_waitcnt lgkmcnt(2)
	v_mfma_f32_16x16x32_bf16 v[78:81], v[130:133], v[204:207], v[78:81]
	s_waitcnt lgkmcnt(1)
	v_mfma_f32_16x16x32_bf16 v[70:73], v[130:133], v[208:211], v[70:73]
	s_waitcnt lgkmcnt(0)
	v_mfma_f32_16x16x32_bf16 v[122:125], v[226:229], v[180:183], v[122:125]
	ds_read_b128 v[130:133], v179 offset:12288
	v_mfma_f32_16x16x32_bf16 v[114:117], v[226:229], v[184:187], v[114:117]
	v_mfma_f32_16x16x32_bf16 v[106:109], v[226:229], v[188:191], v[106:109]
	v_mfma_f32_16x16x32_bf16 v[98:101], v[226:229], v[192:195], v[98:101]
	v_mfma_f32_16x16x32_bf16 v[90:93], v[226:229], v[196:199], v[90:93]
	v_mfma_f32_16x16x32_bf16 v[82:85], v[226:229], v[200:203], v[82:85]
	v_mfma_f32_16x16x32_bf16 v[74:77], v[226:229], v[204:207], v[74:77]
	v_mfma_f32_16x16x32_bf16 v[62:65], v[226:229], v[208:211], v[62:65]
	s_waitcnt lgkmcnt(0)
	v_mfma_f32_16x16x32_bf16 v[54:57], v[130:133], v[180:183], v[54:57]
	ds_read_b128 v[226:229], v179 offset:14336
	v_mfma_f32_16x16x32_bf16 v[46:49], v[130:133], v[184:187], v[46:49]
	v_add_u32_e32 v0, s100, v178
	v_mfma_f32_16x16x32_bf16 v[38:41], v[130:133], v[188:191], v[38:41]
	v_add3_u32 v179, v0, v175, v176
	v_mfma_f32_16x16x32_bf16 v[26:29], v[130:133], v[192:195], v[26:29]
	v_add3_u32 v0, v0, v177, v176
	v_mfma_f32_16x16x32_bf16 v[14:17], v[130:133], v[196:199], v[14:17]
	v_mfma_f32_16x16x32_bf16 v[10:13], v[130:133], v[200:203], v[10:13]
	v_mfma_f32_16x16x32_bf16 v[6:9], v[130:133], v[204:207], v[6:9]
	v_mfma_f32_16x16x32_bf16 v[2:5], v[130:133], v[208:211], v[2:5]
	s_waitcnt lgkmcnt(0)
; #define MFMA16(a, b, c) __builtin_amdgcn_mfma_f32_16x16x32_bf16((a), (b), (c), 0, 0, 0)
; DI void vm_wait0() { asm volatile("s_waitcnt vmcnt(0)" ::: "memory"); }
;   DI unsigned koff(int k) const { return (unsigned)((k >> 6) * EIN + (k & 63)); }
; DI void dma16(const void* g, unsigned char* l) { __builtin_amdgcn_global_load_lds((const unsigned*)g, (lds_u32_t*)(unsigned)(size_t)l, 16, 0, 0); }
; template <class AF, class EF>
; DI void gemm_run(unsigned char* lds, int wv, const AF& af, const bf16_t* __restrict__ Bt, int ldb, int M, int N, int K, const EF& ef, int blk_off) {
;     ...
;     for (int kt = 0; kt < nk; ++kt) {
;       unsigned char* cur = sBase + (kt & 1) * GST;
;       if (kt + 1 < nk) {
;         unsigned char* nxt = sBase + ((kt + 1) & 1) * GST;
;         const int k0 = (kt + 1) << 6;
; #pragma unroll
;         for (int i = 0; i < 4; ++i) {
;           dma16(Ab + aoff[i] + af.koff(k0 + cch), nxt + 32768 + (i * 512 + tid) * 16);
;           dma16(Bt + boff[i] + (unsigned)k0, nxt + (i * 512 + tid) * 16);
;         }
;       }
; #pragma unroll
;       for (int ks = 0; ks < 2; ++ks) {
;         bf16x8 wf[4], xf[8];
; #pragma unroll
;         for (int i = 0; i < 4; ++i) wf[i] = *(const bf16x8*)(cur + (wn * 64 + i * 16 + l15) * 128 + (((ks * 4 + q4) ^ swz) * 16));
; #pragma unroll
;         for (int j = 0; j < 8; ++j) xf[j] = *(const bf16x8*)(cur + 32768 + (wm * 128 + j * 16 + l15) * 128 + (((ks * 4 + q4) ^ swz) * 16));
; #pragma unroll
;         for (int i = 0; i < 4; ++i)
; #pragma unroll
;           for (int j = 0; j < 8; ++j) acc[i][j] = MFMA16(wf[i], xf[j], acc[i][j]);
;       }
;       vm_wait0();
;       __syncthreads();
;     }
	v_mfma_f32_16x16x32_bf16 v[66:69], v[226:229], v[180:183], v[66:69]
	ds_read_b128 v[130:133], v179 offset:8192
	ds_read_b128 v[180:183], v0 offset:40960
	v_mfma_f32_16x16x32_bf16 v[58:61], v[226:229], v[184:187], v[58:61]
	ds_read_b128 v[184:187], v0 offset:43008
	v_mfma_f32_16x16x32_bf16 v[50:53], v[226:229], v[188:191], v[50:53]
	ds_read_b128 v[188:191], v0 offset:45056
	v_mfma_f32_16x16x32_bf16 v[42:45], v[226:229], v[192:195], v[42:45]
	ds_read_b128 v[192:195], v0 offset:47104
	v_mfma_f32_16x16x32_bf16 v[30:33], v[226:229], v[196:199], v[30:33]
	ds_read_b128 v[196:199], v0 offset:49152
	v_mfma_f32_16x16x32_bf16 v[22:25], v[226:229], v[200:203], v[22:25]
	ds_read_b128 v[200:203], v0 offset:51200
	v_mfma_f32_16x16x32_bf16 v[18:21], v[226:229], v[204:207], v[18:21]
	ds_read_b128 v[204:207], v0 offset:53248
	v_mfma_f32_16x16x32_bf16 v[34:37], v[226:229], v[208:211], v[34:37]
	ds_read_b128 v[208:211], v0 offset:55296
	s_waitcnt lgkmcnt(7)
	v_mfma_f32_16x16x32_bf16 v[126:129], v[130:133], v[180:183], v[126:129]
	ds_read_b128 v[226:229], v179 offset:10240
	s_waitcnt lgkmcnt(7)
	v_mfma_f32_16x16x32_bf16 v[118:121], v[130:133], v[184:187], v[118:121]
	s_waitcnt lgkmcnt(6)
	v_mfma_f32_16x16x32_bf16 v[110:113], v[130:133], v[188:191], v[110:113]
	s_waitcnt lgkmcnt(5)
	v_mfma_f32_16x16x32_bf16 v[102:105], v[130:133], v[192:195], v[102:105]
	s_waitcnt lgkmcnt(4)
	v_mfma_f32_16x16x32_bf16 v[94:97], v[130:133], v[196:199], v[94:97]
	s_waitcnt lgkmcnt(3)
	v_mfma_f32_16x16x32_bf16 v[86:89], v[130:133], v[200:203], v[86:89]
	s_waitcnt lgkmcnt(2)
	v_mfma_f32_16x16x32_bf16 v[78:81], v[130:133], v[204:207], v[78:81]
	s_waitcnt lgkmcnt(1)
	v_mfma_f32_16x16x32_bf16 v[70:73], v[130:133], v[208:211], v[70:73]
	s_waitcnt lgkmcnt(0)
	v_mfma_f32_16x16x32_bf16 v[122:125], v[226:229], v[180:183], v[122:125]
	ds_read_b128 v[130:133], v179 offset:12288
	v_mfma_f32_16x16x32_bf16 v[114:117], v[226:229], v[184:187], v[114:117]
	v_mfma_f32_16x16x32_bf16 v[106:109], v[226:229], v[188:191], v[106:109]
	v_mfma_f32_16x16x32_bf16 v[98:101], v[226:229], v[192:195], v[98:101]
	v_mfma_f32_16x16x32_bf16 v[90:93], v[226:229], v[196:199], v[90:93]
	v_mfma_f32_16x16x32_bf16 v[82:85], v[226:229], v[200:203], v[82:85]
	v_mfma_f32_16x16x32_bf16 v[74:77], v[226:229], v[204:207], v[74:77]
	v_mfma_f32_16x16x32_bf16 v[62:65], v[226:229], v[208:211], v[62:65]
	s_waitcnt lgkmcnt(0)
	v_mfma_f32_16x16x32_bf16 v[54:57], v[130:133], v[180:183], v[54:57]
	ds_read_b128 v[226:229], v179 offset:14336
	v_mfma_f32_16x16x32_bf16 v[46:49], v[130:133], v[184:187], v[46:49]
	v_mfma_f32_16x16x32_bf16 v[38:41], v[130:133], v[188:191], v[38:41]
	v_mfma_f32_16x16x32_bf16 v[26:29], v[130:133], v[192:195], v[26:29]
	v_mfma_f32_16x16x32_bf16 v[14:17], v[130:133], v[196:199], v[14:17]
	v_mfma_f32_16x16x32_bf16 v[10:13], v[130:133], v[200:203], v[10:13]
	v_mfma_f32_16x16x32_bf16 v[6:9], v[130:133], v[204:207], v[6:9]
	v_mfma_f32_16x16x32_bf16 v[2:5], v[130:133], v[208:211], v[2:5]
	s_waitcnt vmcnt(0) lgkmcnt(0)
	s_barrier
	s_add_u32 s10, s10, 0x80
	s_addc_u32 s11, s11, 0
	s_add_i32 s15, s15, 0x10000
	s_cmpk_eq_i32 s10, 0x800
	s_cbranch_scc1 .Lmyg1267_tail
	s_add_i32 s100, s15, 0xffff0000
	s_and_b32 s100, s100, 0x10000
	v_add_u32_e32 v0, s100, v174
	v_add3_u32 v179, v0, v175, v176
	v_add3_u32 v0, v0, v177, v176
	s_cmpk_eq_i32 s10, 0x780
	s_cbranch_scc1 .Lmyg1267_nodma
	s_setprio 3
	s_and_b32 s16, s15, 0x10000
	s_add_i32 s16, s16, 0
	s_add_i32 s17, s16, 0x2000
	s_add_i32 s16, s16, 0xa000
	v_add_u32_e32 v224, s16, v136
	v_lshl_add_u64 v[222:223], v[160:161], 0, s[10:11]
	v_readfirstlane_b32 s18, v224
	v_add_u32_e32 v224, s17, v136
	s_mov_b32 m0, s18
	v_readfirstlane_b32 s18, v224
	v_add_u32_e32 v224, s16, v138
	global_load_lds_dwordx4 v[222:223], off
	v_lshl_add_u64 v[222:223], v[152:153], 0, s[10:11]
	s_mov_b32 m0, s18
	v_readfirstlane_b32 s18, v224
	v_add_u32_e32 v224, s17, v138
	global_load_lds_dwordx4 v[222:223], off
	v_lshl_add_u64 v[222:223], v[158:159], 0, s[10:11]
	s_mov_b32 m0, s18
	v_readfirstlane_b32 s18, v224
	v_add_u32_e32 v224, s16, v140
	global_load_lds_dwordx4 v[222:223], off
	v_lshl_add_u64 v[222:223], v[150:151], 0, s[10:11]
	s_mov_b32 m0, s18
	v_readfirstlane_b32 s18, v224
	v_add_u32_e32 v224, s17, v140
	global_load_lds_dwordx4 v[222:223], off
	v_lshl_add_u64 v[222:223], v[156:157], 0, s[10:11]
	s_mov_b32 m0, s18
	v_readfirstlane_b32 s18, v224
	v_add_u32_e32 v224, s16, v142
	global_load_lds_dwordx4 v[222:223], off
	v_lshl_add_u64 v[222:223], v[148:149], 0, s[10:11]
	s_mov_b32 m0, s18
	v_readfirstlane_b32 s16, v224
	v_add_u32_e32 v224, s17, v142
	global_load_lds_dwordx4 v[222:223], off
	v_lshl_add_u64 v[222:223], v[154:155], 0, s[10:11]
	s_mov_b32 m0, s16
	v_readfirstlane_b32 s16, v224
	global_load_lds_dwordx4 v[222:223], off
	v_lshl_add_u64 v[222:223], v[146:147], 0, s[10:11]
	s_mov_b32 m0, s16
	s_nop 0
	global_load_lds_dwordx4 v[222:223], off
	s_setprio 0

; DI void vm_wait0() { asm volatile("s_waitcnt vmcnt(0)" ::: "memory"); }
;   DI unsigned rowoff(int m) const { int combo = m >> 9, n = m & 511, b = combo >> 1, g = combo & 1; return (unsigned)((b * SEQ + 16 * n) * EIN + col0 + g * 64); }
;   DI unsigned koff(int k) const { return (unsigned)((k >> 6) * EIN + (k & 63)); }
; DI void dma16(const void* g, unsigned char* l) { __builtin_amdgcn_global_load_lds((const unsigned*)g, (lds_u32_t*)(unsigned)(size_t)l, 16, 0, 0); }
; template <class AF, class EF>
; DI void gemm_run(unsigned char* lds, int wv, const AF& af, const bf16_t* __restrict__ Bt, int ldb, int M, int N, int K, const EF& ef, int blk_off) {
;     ...
;   for (int tile_ = first; tile_ < ntl_eff; tile_ += tstep) {
;     int nt, mt;
;     if (xmap) { nt = tile_ % ntiles; mt = (tile_ / ntiles) * 8 + ((int)blockIdx.x & 7); }
;     else { nt = tile_ % ntiles; mt = tile_ / ntiles; }
;     const int m0 = mt << 8, n0 = nt << 8;
;     f32x4 acc[4][8];
; #pragma unroll
;     for (int i = 0; i < 4; ++i)
; #pragma unroll
;       for (int j = 0; j < 8; ++j) acc[i][j] = (f32x4){0.f, 0.f, 0.f, 0.f};
;     unsigned aoff[4], boff[4];
;     const bf16_t* Ab = af.base();
; #pragma unroll
;     for (int i = 0; i < 4; ++i) {
;       int row = crow + 64 * i;
;       aoff[i] = af.rowoff(m0 + row);
;       int n = n0 + row; n = n < N ? n : N - 1;
;       boff[i] = (unsigned)(n * ldb + cch);
;     }
;     __syncthreads();
; #pragma unroll
;     for (int i = 0; i < 4; ++i) {
;       dma16(Ab + aoff[i] + af.koff(cch), sBase + 32768 + (i * 512 + tid) * 16);
;       dma16(Bt + boff[i], sBase + (i * 512 + tid) * 16);
;     }
;     vm_wait0();
.LBB0_1278:
	s_ashr_i32 s16, s18, 31
	s_lshr_b32 s16, s16, 30
	s_add_i32 s20, s18, s16
	s_ashr_i32 s19, s20, 2
	s_lshl_b32 s16, s19, 3
	s_or_b32 s21, s16, s78
	v_readlane_b32 s16, v254, 34
	v_readlane_b32 s17, v254, 35
	s_and_b64 s[16:17], s[16:17], exec
	s_cselect_b32 s16, s21, s19
	s_lshl_b32 s19, s16, 8
	s_and_b32 s16, s20, 0xfffffc
	s_sub_i32 s16, s18, s16
	s_lshl_b32 s20, s16, 8
	v_add_u32_e32 v3, s20, v168
	v_min_i32_e32 v3, 0x3ff, v3
	v_lshl_or_b32 v6, v3, 12, v145
	v_add_u32_e32 v3, s20, v169
	v_min_i32_e32 v3, 0x3ff, v3
	v_add_u32_e32 v2, s20, v143
	v_lshl_or_b32 v10, v3, 12, v145
	v_add_u32_e32 v3, s20, v170
	v_add_lshl_u32 v0, s19, v143, 12
	v_min_i32_e32 v2, 0x3ff, v2
	v_min_i32_e32 v3, 0x3ff, v3
	v_lshl_or_b32 v2, v2, 12, v145
	v_lshl_or_b32 v14, v3, 12, v145
	v_lshlrev_b64 v[16:17], 1, v[0:1]
	v_readfirstlane_b32 s16, v171
	v_mov_b32_e32 v3, v1
	v_add_lshl_u32 v4, s19, v168, 12
	v_lshl_add_u64 v[18:19], v[138:139], 0, v[16:17]
	s_mov_b32 m0, s16
	v_lshlrev_b64 v[2:3], 1, v[2:3]
	v_readfirstlane_b32 s16, v172
	v_mov_b32_e32 v5, v1
	s_waitcnt lgkmcnt(0)
	s_barrier
	global_load_lds_dwordx4 v[18:19], off
	v_lshl_add_u64 v[18:19], s[4:5], 0, v[2:3]
	s_mov_b32 m0, s16
	v_lshlrev_b64 v[4:5], 1, v[4:5]
	v_readfirstlane_b32 s16, v173
	v_mov_b32_e32 v7, v1
	v_add_lshl_u32 v8, s19, v169, 12
	global_load_lds_dwordx4 v[18:19], off
	v_lshl_add_u64 v[18:19], v[138:139], 0, v[4:5]
	s_mov_b32 m0, s16
	v_lshlrev_b64 v[6:7], 1, v[6:7]
	v_readfirstlane_b32 s16, v174
	v_mov_b32_e32 v9, v1
	global_load_lds_dwordx4 v[18:19], off
	v_lshl_add_u64 v[18:19], s[4:5], 0, v[6:7]
	s_mov_b32 m0, s16
	v_lshlrev_b64 v[8:9], 1, v[8:9]
	v_readfirstlane_b32 s16, v175
	v_mov_b32_e32 v11, v1
	v_add_lshl_u32 v12, s19, v170, 12
	global_load_lds_dwordx4 v[18:19], off
	v_lshl_add_u64 v[18:19], v[138:139], 0, v[8:9]
	s_mov_b32 m0, s16
	v_lshlrev_b64 v[10:11], 1, v[10:11]
	v_readfirstlane_b32 s16, v176
	v_mov_b32_e32 v13, v1
	global_load_lds_dwordx4 v[18:19], off
	v_lshl_add_u64 v[18:19], s[4:5], 0, v[10:11]
	s_mov_b32 m0, s16
	v_lshlrev_b64 v[12:13], 1, v[12:13]
	v_readfirstlane_b32 s16, v177
	v_mov_b32_e32 v15, v1
	global_load_lds_dwordx4 v[18:19], off
	v_lshl_add_u64 v[18:19], v[138:139], 0, v[12:13]
	s_mov_b32 m0, s16
	v_lshlrev_b64 v[14:15], 1, v[14:15]
	v_readfirstlane_b32 s16, v178
	global_load_lds_dwordx4 v[18:19], off
	v_lshl_add_u64 v[18:19], s[4:5], 0, v[14:15]
	s_mov_b32 m0, s16
	v_lshl_add_u64 v[156:157], s[14:15], 0, v[2:3]
	global_load_lds_dwordx4 v[18:19], off
	v_mov_b32_e32 v2, 0
	v_lshl_add_u64 v[150:151], s[14:15], 0, v[14:15]
	v_lshl_add_u64 v[152:153], s[14:15], 0, v[10:11]
	v_lshl_add_u64 v[154:155], s[14:15], 0, v[6:7]
	v_lshl_add_u64 v[158:159], v[148:149], 0, v[12:13]
	v_lshl_add_u64 v[160:161], v[148:149], 0, v[8:9]
	v_lshl_add_u64 v[164:165], v[148:149], 0, v[4:5]
	v_lshl_add_u64 v[166:167], v[148:149], 0, v[16:17]
	s_mov_b32 s21, 0
	s_mov_b64 s[16:17], 0
	s_mov_b32 s22, 0x10000
	v_mov_b32_e32 v3, v2
	v_mov_b32_e32 v4, v2
	v_mov_b32_e32 v5, v2
	v_mov_b32_e32 v6, v2
	v_mov_b32_e32 v7, v2
	v_mov_b32_e32 v8, v2
	v_mov_b32_e32 v9, v2
	v_mov_b32_e32 v10, v2
	v_mov_b32_e32 v11, v2
	v_mov_b32_e32 v12, v2
	v_mov_b32_e32 v13, v2
	v_mov_b32_e32 v14, v2
	v_mov_b32_e32 v15, v2
	v_mov_b32_e32 v16, v2
	v_mov_b32_e32 v17, v2
	v_mov_b32_e32 v30, v2
	v_mov_b32_e32 v31, v2
	v_mov_b32_e32 v32, v2
	v_mov_b32_e32 v33, v2
	v_mov_b32_e32 v42, v2
	v_mov_b32_e32 v43, v2
	v_mov_b32_e32 v44, v2
	v_mov_b32_e32 v45, v2
	v_mov_b32_e32 v50, v2
	v_mov_b32_e32 v51, v2
	v_mov_b32_e32 v52, v2
	v_mov_b32_e32 v53, v2
	v_mov_b32_e32 v58, v2
	v_mov_b32_e32 v59, v2
	v_mov_b32_e32 v60, v2
	v_mov_b32_e32 v61, v2
	v_mov_b32_e32 v66, v2
	v_mov_b32_e32 v67, v2
	v_mov_b32_e32 v68, v2
	v_mov_b32_e32 v69, v2
	v_mov_b32_e32 v74, v2
	v_mov_b32_e32 v75, v2
	v_mov_b32_e32 v76, v2
	v_mov_b32_e32 v77, v2
	v_mov_b32_e32 v82, v2
	v_mov_b32_e32 v83, v2
	v_mov_b32_e32 v84, v2
	v_mov_b32_e32 v85, v2
	v_mov_b32_e32 v90, v2
	v_mov_b32_e32 v91, v2
	v_mov_b32_e32 v92, v2
	v_mov_b32_e32 v93, v2
	v_mov_b32_e32 v98, v2
	v_mov_b32_e32 v99, v2
	v_mov_b32_e32 v100, v2
	v_mov_b32_e32 v101, v2
	v_mov_b32_e32 v106, v2
	v_mov_b32_e32 v107, v2
	v_mov_b32_e32 v108, v2
	v_mov_b32_e32 v109, v2
	v_mov_b32_e32 v114, v2
	v_mov_b32_e32 v115, v2
	v_mov_b32_e32 v116, v2
	v_mov_b32_e32 v117, v2
	v_mov_b32_e32 v122, v2
	v_mov_b32_e32 v123, v2
	v_mov_b32_e32 v124, v2
	v_mov_b32_e32 v125, v2
	v_mov_b32_e32 v70, v2
	v_mov_b32_e32 v71, v2
	v_mov_b32_e32 v72, v2
	v_mov_b32_e32 v73, v2
	v_mov_b32_e32 v78, v2
	v_mov_b32_e32 v79, v2
	v_mov_b32_e32 v80, v2
	v_mov_b32_e32 v81, v2
	v_mov_b32_e32 v86, v2
	v_mov_b32_e32 v87, v2
	v_mov_b32_e32 v88, v2
	v_mov_b32_e32 v89, v2
	v_mov_b32_e32 v94, v2
	v_mov_b32_e32 v95, v2
	v_mov_b32_e32 v96, v2
	v_mov_b32_e32 v97, v2
	v_mov_b32_e32 v102, v2
	v_mov_b32_e32 v103, v2
	v_mov_b32_e32 v104, v2
	v_mov_b32_e32 v105, v2
	v_mov_b32_e32 v110, v2
	v_mov_b32_e32 v111, v2
	v_mov_b32_e32 v112, v2
	v_mov_b32_e32 v113, v2
	v_mov_b32_e32 v118, v2
	v_mov_b32_e32 v119, v2
	v_mov_b32_e32 v120, v2
	v_mov_b32_e32 v121, v2
	v_mov_b32_e32 v126, v2
	v_mov_b32_e32 v127, v2
	v_mov_b32_e32 v128, v2
	v_mov_b32_e32 v129, v2
	v_mov_b32_e32 v62, v2
	v_mov_b32_e32 v63, v2
	v_mov_b32_e32 v64, v2
	v_mov_b32_e32 v65, v2
	v_mov_b32_e32 v54, v2
	v_mov_b32_e32 v55, v2
	v_mov_b32_e32 v56, v2
	v_mov_b32_e32 v57, v2
	v_mov_b32_e32 v46, v2
	v_mov_b32_e32 v47, v2
	v_mov_b32_e32 v48, v2
	v_mov_b32_e32 v49, v2
	v_mov_b32_e32 v38, v2
	v_mov_b32_e32 v39, v2
	v_mov_b32_e32 v40, v2
	v_mov_b32_e32 v41, v2
	v_mov_b32_e32 v26, v2
	v_mov_b32_e32 v27, v2
	v_mov_b32_e32 v28, v2
	v_mov_b32_e32 v29, v2
	v_mov_b32_e32 v22, v2
	v_mov_b32_e32 v23, v2
; #define MFMA16(a, b, c) __builtin_amdgcn_mfma_f32_16x16x32_bf16((a), (b), (c), 0, 0, 0)
; DI void vm_wait0() { asm volatile("s_waitcnt vmcnt(0)" ::: "memory"); }
;   DI unsigned koff(int k) const { return (unsigned)((k >> 6) * EIN + (k & 63)); }
; DI void dma16(const void* g, unsigned char* l) { __builtin_amdgcn_global_load_lds((const unsigned*)g, (lds_u32_t*)(unsigned)(size_t)l, 16, 0, 0); }
; template <class AF, class EF>
; DI void gemm_run(unsigned char* lds, int wv, const AF& af, const bf16_t* __restrict__ Bt, int ldb, int M, int N, int K, const EF& ef, int blk_off) {
;     ...
;     __syncthreads();
; #pragma unroll
;     for (int i = 0; i < 4; ++i) {
;       dma16(Ab + aoff[i] + af.koff(cch), sBase + 32768 + (i * 512 + tid) * 16);
;       dma16(Bt + boff[i], sBase + (i * 512 + tid) * 16);
;     }
;     vm_wait0();
;     __syncthreads();
; #pragma unroll 1
;     for (int kt = 0; kt < nk; ++kt) {
;       unsigned char* cur = sBase + (kt & 1) * GST;
;       if (kt + 1 < nk) {
;         unsigned char* nxt = sBase + ((kt + 1) & 1) * GST;
;         const int k0 = (kt + 1) << 6;
; #pragma unroll
;         for (int i = 0; i < 4; ++i) {
;           dma16(Ab + aoff[i] + af.koff(k0 + cch), nxt + 32768 + (i * 512 + tid) * 16);
;           dma16(Bt + boff[i] + (unsigned)k0, nxt + (i * 512 + tid) * 16);
;         }
;       }
; #pragma unroll
;       for (int ks = 0; ks < 2; ++ks) {
;         bf16x8 wf[4], xf[8];
; #pragma unroll
;         for (int i = 0; i < 4; ++i) wf[i] = *(const bf16x8*)(cur + (wn * 64 + i * 16 + l15) * 128 + (((ks * 4 + q4) ^ swz) * 16));
; #pragma unroll
;         for (int j = 0; j < 8; ++j) xf[j] = *(const bf16x8*)(cur + 32768 + (wm * 128 + j * 16 + l15) * 128 + (((ks * 4 + q4) ^ swz) * 16));
; #pragma unroll
;         for (int i = 0; i < 4; ++i)
; #pragma unroll
;           for (int j = 0; j < 8; ++j) acc[i][j] = MFMA16(wf[i], xf[j], acc[i][j]);
	v_mov_b32_e32 v24, v2
	v_mov_b32_e32 v25, v2
	v_mov_b32_e32 v34, v2
	v_mov_b32_e32 v35, v2
	v_mov_b32_e32 v36, v2
	v_mov_b32_e32 v37, v2
	v_mov_b32_e32 v18, v2
	v_mov_b32_e32 v19, v2
	v_mov_b32_e32 v20, v2
	v_mov_b32_e32 v21, v2
	s_and_b32 s23, s22, 0x10000
	s_add_i32 s23, s23, 0
	s_add_i32 s24, s23, 0x2000
	s_add_i32 s23, s23, 0xa000
	v_add_u32_e32 v224, s23, v140
	v_lshl_add_u64 v[222:223], v[166:167], 0, s[16:17]
	v_readfirstlane_b32 s25, v224
	v_add_u32_e32 v224, s24, v140
	s_mov_b32 m0, s25
	v_readfirstlane_b32 s25, v224
	v_add_u32_e32 v224, s23, v142
	global_load_lds_dwordx4 v[222:223], off
	v_lshl_add_u64 v[222:223], v[156:157], 0, s[16:17]
	s_mov_b32 m0, s25
	v_readfirstlane_b32 s25, v224
	v_add_u32_e32 v224, s24, v142
	global_load_lds_dwordx4 v[222:223], off
	v_lshl_add_u64 v[222:223], v[164:165], 0, s[16:17]
	s_mov_b32 m0, s25
	v_readfirstlane_b32 s25, v224
	v_add_u32_e32 v224, s23, v144
	global_load_lds_dwordx4 v[222:223], off
	v_lshl_add_u64 v[222:223], v[154:155], 0, s[16:17]
	s_mov_b32 m0, s25
	v_readfirstlane_b32 s25, v224
	v_add_u32_e32 v224, s24, v144
	global_load_lds_dwordx4 v[222:223], off
	v_lshl_add_u64 v[222:223], v[160:161], 0, s[16:17]
	s_mov_b32 m0, s25
	v_readfirstlane_b32 s25, v224
	v_add_u32_e32 v224, s23, v146
	global_load_lds_dwordx4 v[222:223], off
	v_lshl_add_u64 v[222:223], v[152:153], 0, s[16:17]
	s_mov_b32 m0, s25
	v_readfirstlane_b32 s23, v224
	v_add_u32_e32 v224, s24, v146
	global_load_lds_dwordx4 v[222:223], off
	v_lshl_add_u64 v[222:223], v[158:159], 0, s[16:17]
	s_mov_b32 m0, s23
	v_readfirstlane_b32 s23, v224
	global_load_lds_dwordx4 v[222:223], off
	v_lshl_add_u64 v[222:223], v[150:151], 0, s[16:17]
	s_mov_b32 m0, s23
	s_nop 0
	global_load_lds_dwordx4 v[222:223], off
	s_waitcnt vmcnt(8) lgkmcnt(0)
	s_barrier
	s_branch .LBB0_1280
.LBB0_1280:
	s_add_i32 s100, s22, 0xffff0000
	s_and_b32 s100, s100, 0x10000
	v_add_u32_e32 v0, s100, v179
	v_add3_u32 v212, v0, v180, v181
	v_add3_u32 v0, v0, v182, v181
	ds_read_b128 v[130:133], v212 offset:8192
	ds_read_b128 v[184:187], v0 offset:43008
	ds_read_b128 v[134:137], v0 offset:40960
	ds_read_b128 v[188:191], v0 offset:45056
	ds_read_b128 v[192:195], v0 offset:47104
	ds_read_b128 v[196:199], v0 offset:49152
	ds_read_b128 v[200:203], v0 offset:51200
	ds_read_b128 v[204:207], v0 offset:53248
	ds_read_b128 v[208:211], v0 offset:55296
.Lmyg1279_loop:
	s_waitcnt lgkmcnt(7)
	v_mfma_f32_16x16x32_bf16 v[118:121], v[130:133], v[184:187], v[118:121]
	ds_read_b128 v[226:229], v212 offset:10240
	s_waitcnt lgkmcnt(7)
	v_mfma_f32_16x16x32_bf16 v[126:129], v[130:133], v[134:137], v[126:129]
	s_waitcnt lgkmcnt(6)
	v_mfma_f32_16x16x32_bf16 v[110:113], v[130:133], v[188:191], v[110:113]
	s_waitcnt lgkmcnt(5)
	v_mfma_f32_16x16x32_bf16 v[102:105], v[130:133], v[192:195], v[102:105]
	s_waitcnt lgkmcnt(4)
	v_mfma_f32_16x16x32_bf16 v[94:97], v[130:133], v[196:199], v[94:97]
	s_waitcnt lgkmcnt(3)
	v_mfma_f32_16x16x32_bf16 v[86:89], v[130:133], v[200:203], v[86:89]
	s_waitcnt lgkmcnt(2)
	v_mfma_f32_16x16x32_bf16 v[78:81], v[130:133], v[204:207], v[78:81]
	s_waitcnt lgkmcnt(1)
	v_mfma_f32_16x16x32_bf16 v[70:73], v[130:133], v[208:211], v[70:73]
	s_waitcnt lgkmcnt(0)
	v_mfma_f32_16x16x32_bf16 v[122:125], v[226:229], v[134:137], v[122:125]
	ds_read_b128 v[130:133], v212 offset:12288
	v_mfma_f32_16x16x32_bf16 v[114:117], v[226:229], v[184:187], v[114:117]
	v_mfma_f32_16x16x32_bf16 v[106:109], v[226:229], v[188:191], v[106:109]
	v_mfma_f32_16x16x32_bf16 v[98:101], v[226:229], v[192:195], v[98:101]
	v_mfma_f32_16x16x32_bf16 v[90:93], v[226:229], v[196:199], v[90:93]
	v_mfma_f32_16x16x32_bf16 v[82:85], v[226:229], v[200:203], v[82:85]
	v_mfma_f32_16x16x32_bf16 v[74:77], v[226:229], v[204:207], v[74:77]
	v_mfma_f32_16x16x32_bf16 v[66:69], v[226:229], v[208:211], v[66:69]
	s_waitcnt lgkmcnt(0)
	v_mfma_f32_16x16x32_bf16 v[58:61], v[130:133], v[134:137], v[58:61]
	ds_read_b128 v[226:229], v212 offset:14336
	v_mfma_f32_16x16x32_bf16 v[50:53], v[130:133], v[184:187], v[50:53]
	v_add_u32_e32 v0, s100, v183
	v_mfma_f32_16x16x32_bf16 v[42:45], v[130:133], v[188:191], v[42:45]
	v_add3_u32 v212, v0, v180, v181
	v_mfma_f32_16x16x32_bf16 v[30:33], v[130:133], v[192:195], v[30:33]
	v_add3_u32 v0, v0, v182, v181
	v_mfma_f32_16x16x32_bf16 v[14:17], v[130:133], v[196:199], v[14:17]
	v_mfma_f32_16x16x32_bf16 v[10:13], v[130:133], v[200:203], v[10:13]
	v_mfma_f32_16x16x32_bf16 v[6:9], v[130:133], v[204:207], v[6:9]
	v_mfma_f32_16x16x32_bf16 v[2:5], v[130:133], v[208:211], v[2:5]
	s_waitcnt lgkmcnt(0)
; #define MFMA16(a, b, c) __builtin_amdgcn_mfma_f32_16x16x32_bf16((a), (b), (c), 0, 0, 0)
; DI void vm_wait0() { asm volatile("s_waitcnt vmcnt(0)" ::: "memory"); }
;   DI unsigned koff(int k) const { return (unsigned)((k >> 6) * EIN + (k & 63)); }
; DI void dma16(const void* g, unsigned char* l) { __builtin_amdgcn_global_load_lds((const unsigned*)g, (lds_u32_t*)(unsigned)(size_t)l, 16, 0, 0); }
; template <class AF, class EF>
; DI void gemm_run(unsigned char* lds, int wv, const AF& af, const bf16_t* __restrict__ Bt, int ldb, int M, int N, int K, const EF& ef, int blk_off) {
;     ...
;     for (int kt = 0; kt < nk; ++kt) {
;       unsigned char* cur = sBase + (kt & 1) * GST;
;       if (kt + 1 < nk) {
;         unsigned char* nxt = sBase + ((kt + 1) & 1) * GST;
;         const int k0 = (kt + 1) << 6;
; #pragma unroll
;         for (int i = 0; i < 4; ++i) {
;           dma16(Ab + aoff[i] + af.koff(k0 + cch), nxt + 32768 + (i * 512 + tid) * 16);
;           dma16(Bt + boff[i] + (unsigned)k0, nxt + (i * 512 + tid) * 16);
;         }
;       }
; #pragma unroll
;       for (int ks = 0; ks < 2; ++ks) {
;         bf16x8 wf[4], xf[8];
; #pragma unroll
;         for (int i = 0; i < 4; ++i) wf[i] = *(const bf16x8*)(cur + (wn * 64 + i * 16 + l15) * 128 + (((ks * 4 + q4) ^ swz) * 16));
; #pragma unroll
;         for (int j = 0; j < 8; ++j) xf[j] = *(const bf16x8*)(cur + 32768 + (wm * 128 + j * 16 + l15) * 128 + (((ks * 4 + q4) ^ swz) * 16));
; #pragma unroll
;         for (int i = 0; i < 4; ++i)
; #pragma unroll
;           for (int j = 0; j < 8; ++j) acc[i][j] = MFMA16(wf[i], xf[j], acc[i][j]);
;       }
;       vm_wait0();
;       __syncthreads();
;     }
	v_mfma_f32_16x16x32_bf16 v[54:57], v[226:229], v[184:187], v[54:57]
	ds_read_b128 v[130:133], v212 offset:8192
	ds_read_b128 v[184:187], v0 offset:43008
	v_mfma_f32_16x16x32_bf16 v[62:65], v[226:229], v[134:137], v[62:65]
	ds_read_b128 v[134:137], v0 offset:40960
	v_mfma_f32_16x16x32_bf16 v[46:49], v[226:229], v[188:191], v[46:49]
	ds_read_b128 v[188:191], v0 offset:45056
	v_mfma_f32_16x16x32_bf16 v[38:41], v[226:229], v[192:195], v[38:41]
	ds_read_b128 v[192:195], v0 offset:47104
	v_mfma_f32_16x16x32_bf16 v[26:29], v[226:229], v[196:199], v[26:29]
	ds_read_b128 v[196:199], v0 offset:49152
	v_mfma_f32_16x16x32_bf16 v[22:25], v[226:229], v[200:203], v[22:25]
	ds_read_b128 v[200:203], v0 offset:51200
	v_mfma_f32_16x16x32_bf16 v[34:37], v[226:229], v[204:207], v[34:37]
	ds_read_b128 v[204:207], v0 offset:53248
	v_mfma_f32_16x16x32_bf16 v[18:21], v[226:229], v[208:211], v[18:21]
	ds_read_b128 v[208:211], v0 offset:55296
	s_waitcnt lgkmcnt(7)
	v_mfma_f32_16x16x32_bf16 v[118:121], v[130:133], v[184:187], v[118:121]
	ds_read_b128 v[226:229], v212 offset:10240
	s_waitcnt lgkmcnt(7)
	v_mfma_f32_16x16x32_bf16 v[126:129], v[130:133], v[134:137], v[126:129]
	s_waitcnt lgkmcnt(6)
	v_mfma_f32_16x16x32_bf16 v[110:113], v[130:133], v[188:191], v[110:113]
	s_waitcnt lgkmcnt(5)
	v_mfma_f32_16x16x32_bf16 v[102:105], v[130:133], v[192:195], v[102:105]
	s_waitcnt lgkmcnt(4)
	v_mfma_f32_16x16x32_bf16 v[94:97], v[130:133], v[196:199], v[94:97]
	s_waitcnt lgkmcnt(3)
	v_mfma_f32_16x16x32_bf16 v[86:89], v[130:133], v[200:203], v[86:89]
	s_waitcnt lgkmcnt(2)
	v_mfma_f32_16x16x32_bf16 v[78:81], v[130:133], v[204:207], v[78:81]
	s_waitcnt lgkmcnt(1)
	v_mfma_f32_16x16x32_bf16 v[70:73], v[130:133], v[208:211], v[70:73]
	s_waitcnt lgkmcnt(0)
	v_mfma_f32_16x16x32_bf16 v[122:125], v[226:229], v[134:137], v[122:125]
	ds_read_b128 v[130:133], v212 offset:12288
	v_mfma_f32_16x16x32_bf16 v[114:117], v[226:229], v[184:187], v[114:117]
	v_mfma_f32_16x16x32_bf16 v[106:109], v[226:229], v[188:191], v[106:109]
	v_mfma_f32_16x16x32_bf16 v[98:101], v[226:229], v[192:195], v[98:101]
	v_mfma_f32_16x16x32_bf16 v[90:93], v[226:229], v[196:199], v[90:93]
	v_mfma_f32_16x16x32_bf16 v[82:85], v[226:229], v[200:203], v[82:85]
	v_mfma_f32_16x16x32_bf16 v[74:77], v[226:229], v[204:207], v[74:77]
	v_mfma_f32_16x16x32_bf16 v[66:69], v[226:229], v[208:211], v[66:69]
	s_waitcnt lgkmcnt(0)
	v_mfma_f32_16x16x32_bf16 v[58:61], v[130:133], v[134:137], v[58:61]
	ds_read_b128 v[226:229], v212 offset:14336
	v_mfma_f32_16x16x32_bf16 v[50:53], v[130:133], v[184:187], v[50:53]
	v_mfma_f32_16x16x32_bf16 v[42:45], v[130:133], v[188:191], v[42:45]
	v_mfma_f32_16x16x32_bf16 v[30:33], v[130:133], v[192:195], v[30:33]
	v_mfma_f32_16x16x32_bf16 v[14:17], v[130:133], v[196:199], v[14:17]
	v_mfma_f32_16x16x32_bf16 v[10:13], v[130:133], v[200:203], v[10:13]
	v_mfma_f32_16x16x32_bf16 v[6:9], v[130:133], v[204:207], v[6:9]
	v_mfma_f32_16x16x32_bf16 v[2:5], v[130:133], v[208:211], v[2:5]
	s_waitcnt vmcnt(0) lgkmcnt(0)
	s_barrier
	s_add_u32 s16, s16, 0x80
	s_addc_u32 s17, s17, 0
	s_add_i32 s22, s22, 0x10000
	s_add_i32 s21, s21, 1
	s_cmpk_eq_i32 s16, 0x2000
	s_cbranch_scc1 .Lmyg1279_tail
	s_add_i32 s100, s22, 0xffff0000
	s_and_b32 s100, s100, 0x10000
	v_add_u32_e32 v0, s100, v179
	v_add3_u32 v212, v0, v180, v181
	v_add3_u32 v0, v0, v182, v181
	s_cmp_gt_u32 s21, 62
	s_cbranch_scc1 .Lmyg1279_nodma
	s_setprio 3
	s_and_b32 s23, s22, 0x10000
	s_add_i32 s23, s23, 0
	s_add_i32 s24, s23, 0x2000
	s_add_i32 s23, s23, 0xa000
	v_add_u32_e32 v224, s23, v140
	v_lshl_add_u64 v[222:223], v[166:167], 0, s[16:17]
	v_readfirstlane_b32 s25, v224
	v_add_u32_e32 v224, s24, v140
	s_mov_b32 m0, s25
	v_readfirstlane_b32 s25, v224
	v_add_u32_e32 v224, s23, v142
	global_load_lds_dwordx4 v[222:223], off
	v_lshl_add_u64 v[222:223], v[156:157], 0, s[16:17]
	s_mov_b32 m0, s25
	v_readfirstlane_b32 s25, v224
	v_add_u32_e32 v224, s24, v142
	global_load_lds_dwordx4 v[222:223], off
	v_lshl_add_u64 v[222:223], v[164:165], 0, s[16:17]
	s_mov_b32 m0, s25
	v_readfirstlane_b32 s25, v224
	v_add_u32_e32 v224, s23, v144
	global_load_lds_dwordx4 v[222:223], off
	v_lshl_add_u64 v[222:223], v[154:155], 0, s[16:17]
	s_mov_b32 m0, s25
	v_readfirstlane_b32 s25, v224
	v_add_u32_e32 v224, s24, v144
	global_load_lds_dwordx4 v[222:223], off
	v_lshl_add_u64 v[222:223], v[160:161], 0, s[16:17]
	s_mov_b32 m0, s25
	v_readfirstlane_b32 s25, v224
	v_add_u32_e32 v224, s23, v146
	global_load_lds_dwordx4 v[222:223], off
	v_lshl_add_u64 v[222:223], v[152:153], 0, s[16:17]
	s_mov_b32 m0, s25
	v_readfirstlane_b32 s23, v224
	v_add_u32_e32 v224, s24, v146
	global_load_lds_dwordx4 v[222:223], off
	v_lshl_add_u64 v[222:223], v[158:159], 0, s[16:17]
	s_mov_b32 m0, s23
	v_readfirstlane_b32 s23, v224
	global_load_lds_dwordx4 v[222:223], off
	v_lshl_add_u64 v[222:223], v[150:151], 0, s[16:17]
	s_mov_b32 m0, s23
	s_nop 0
	global_load_lds_dwordx4 v[222:223], off
	s_setprio 0
